# K-loop load segments slimmed: merged vmcnt/lgkmcnt waits, no s_setprio, LDS read bases in spare VGPRs (GEMM1-3), on top of nop-fill
# baseline (speedup 1.0000x reference)
.LBB0_271:
	s_ashr_i32 s63, s62, 31
	s_lshl_b64 s[0:1], s[62:63], 20
	s_add_u32 s66, s49, s0
	s_addc_u32 s67, s82, s1
	s_and_b64 s[0:1], s[4:5], exec
	s_cselect_b32 s0, s67, s75
	s_cselect_b32 s1, s66, s74
	s_ashr_i32 s65, s64, 31
	s_lshl_b64 s[68:69], s[64:65], 20
	s_add_u32 s68, s45, s68
	s_addc_u32 s69, s47, s69
	s_and_b64 s[78:79], s[4:5], exec
	s_cselect_b32 s3, s69, s77
	s_cselect_b32 s63, s68, s76
	s_add_u32 s74, s74, 0x80080
	s_addc_u32 s75, s75, 0
	s_add_u32 s65, s76, 0x100
	s_addc_u32 s71, s77, 0
	s_mov_b32 s90, -2
	s_waitcnt vmcnt(0)
	ds_read_b128 v[146:149], v166
	ds_read_b128 v[150:153], v166 offset:1024
	ds_read_b128 v[154:157], v166 offset:2048
	ds_read_b128 v[170:173], v166 offset:3072
	ds_read_b128 v[174:177], v167
	ds_read_b128 v[178:181], v167 offset:1024
	ds_read_b128 v[182:185], v167 offset:2048
	ds_read_b128 v[186:189], v167 offset:3072
	s_add_u32 s76, s74, 0xfff80080
	s_addc_u32 s77, s75, -1
	s_cmp_eq_u32 s90, 28
	s_cselect_b32 s79, s0, s77
	s_cselect_b32 s78, s1, s76
	s_cselect_b32 s77, s3, s71
	s_cselect_b32 s76, s63, s65
	s_add_i32 m0, s31, 0xc000
	ds_read_b128 v[190:193], v168
	ds_read_b128 v[194:197], v168 offset:1024
	ds_read_b128 v[198:201], v168 offset:2048
	ds_read_b128 v[202:205], v168 offset:3072
	ds_read_b128 v[206:209], v168 offset:4096
	ds_read_b128 v[214:217], v168 offset:5120
	ds_read_b128 v[218:221], v168 offset:6144
	global_load_lds_dwordx4 v138, s[74:75]
	s_add_i32 m0, s31, 0xe000
	ds_read_b128 v[222:225], v168 offset:7168
	global_load_lds_dwordx4 v140, s[74:75]
	s_waitcnt vmcnt(8) lgkmcnt(0)
	s_barrier
	v_mfma_f32_16x16x32_bf16 v[124:127], v[146:149], v[190:193], 0
	v_mfma_f32_16x16x32_bf16 v[120:123], v[154:157], v[190:193], 0
	v_mfma_f32_16x16x32_bf16 v[108:111], v[146:149], v[198:201], 0
	v_mfma_f32_16x16x32_bf16 v[104:107], v[154:157], v[198:201], 0
	v_mfma_f32_16x16x32_bf16 v[92:95], v[146:149], v[206:209], 0
	v_mfma_f32_16x16x32_bf16 v[88:91], v[154:157], v[206:209], 0
	v_mfma_f32_16x16x32_bf16 v[76:79], v[146:149], v[218:221], 0
	v_mfma_f32_16x16x32_bf16 v[72:75], v[154:157], v[218:221], 0
	v_mfma_f32_16x16x32_bf16 v[124:127], v[150:153], v[194:197], v[124:127]
	v_mfma_f32_16x16x32_bf16 v[120:123], v[170:173], v[194:197], v[120:123]
	v_mfma_f32_16x16x32_bf16 v[108:111], v[150:153], v[202:205], v[108:111]
	v_mfma_f32_16x16x32_bf16 v[104:107], v[170:173], v[202:205], v[104:107]
	v_mfma_f32_16x16x32_bf16 v[92:95], v[150:153], v[214:217], v[92:95]
	v_mfma_f32_16x16x32_bf16 v[88:91], v[170:173], v[214:217], v[88:91]
	v_mfma_f32_16x16x32_bf16 v[76:79], v[150:153], v[222:225], v[76:79]
	v_mfma_f32_16x16x32_bf16 v[72:75], v[170:173], v[222:225], v[72:75]
	v_mfma_f32_16x16x32_bf16 v[116:119], v[174:177], v[190:193], 0
	v_mfma_f32_16x16x32_bf16 v[112:115], v[182:185], v[190:193], 0
	v_mfma_f32_16x16x32_bf16 v[100:103], v[174:177], v[198:201], 0
	v_mfma_f32_16x16x32_bf16 v[96:99], v[182:185], v[198:201], 0
	v_mfma_f32_16x16x32_bf16 v[84:87], v[174:177], v[206:209], 0
	v_mfma_f32_16x16x32_bf16 v[80:83], v[182:185], v[206:209], 0
	v_mfma_f32_16x16x32_bf16 v[68:71], v[174:177], v[218:221], 0
	v_mfma_f32_16x16x32_bf16 v[64:67], v[182:185], v[218:221], 0
	v_mfma_f32_16x16x32_bf16 v[116:119], v[178:181], v[194:197], v[116:119]
	v_mfma_f32_16x16x32_bf16 v[112:115], v[186:189], v[194:197], v[112:115]
	v_mfma_f32_16x16x32_bf16 v[100:103], v[178:181], v[202:205], v[100:103]
	v_mfma_f32_16x16x32_bf16 v[96:99], v[186:189], v[202:205], v[96:99]
	v_mfma_f32_16x16x32_bf16 v[84:87], v[178:181], v[214:217], v[84:87]
	v_mfma_f32_16x16x32_bf16 v[80:83], v[186:189], v[214:217], v[80:83]
	v_mfma_f32_16x16x32_bf16 v[68:71], v[178:181], v[222:225], v[68:71]
	v_mfma_f32_16x16x32_bf16 v[64:67], v[186:189], v[222:225], v[64:67]
	s_barrier
	s_add_i32 s91, s81, s30
	s_add_u32 s98, s76, s34
	s_addc_u32 s99, s77, s35
	s_mov_b32 m0, s91
	ds_read_b128 v[190:193], v168 offset:16384
	ds_read_b128 v[194:197], v168 offset:17408
	ds_read_b128 v[198:201], v168 offset:18432
	ds_read_b128 v[202:205], v168 offset:19456
	ds_read_b128 v[206:209], v168 offset:20480
	global_load_lds_dwordx4 v130, s[76:77]
	s_add_i32 m0, s91, 0x2000
	s_add_u32 s92, s76, 0x80000
	s_addc_u32 s93, s77, 0
	s_add_i32 s91, s83, s30
	global_load_lds_dwordx4 v134, s[76:77]
	s_mov_b32 m0, s91
	s_add_u32 s100, s78, s34
	s_addc_u32 s101, s79, s35
	global_load_lds_dwordx4 v130, s[92:93]
	s_add_i32 m0, s91, 0x2000
	ds_read_b128 v[222:225], v168 offset:23552
	global_load_lds_dwordx4 v134, s[92:93]
	s_mov_b32 m0, s31
	ds_read_b128 v[218:221], v168 offset:22528
	global_load_lds_dwordx4 v128, s[78:79]
	s_mov_b32 m0, s51
	ds_read_b128 v[214:217], v168 offset:21504
	global_load_lds_dwordx4 v132, s[78:79]
	s_waitcnt vmcnt(8) lgkmcnt(0)
	s_barrier
	v_mfma_f32_16x16x32_bf16 v[60:63], v[146:149], v[190:193], 0
	v_mfma_f32_16x16x32_bf16 v[56:59], v[154:157], v[190:193], 0
	v_mfma_f32_16x16x32_bf16 v[44:47], v[146:149], v[198:201], 0
	v_mfma_f32_16x16x32_bf16 v[40:43], v[154:157], v[198:201], 0
	v_mfma_f32_16x16x32_bf16 v[28:31], v[146:149], v[206:209], 0
	v_mfma_f32_16x16x32_bf16 v[24:27], v[154:157], v[206:209], 0
	v_mfma_f32_16x16x32_bf16 v[12:15], v[146:149], v[218:221], 0
	v_mfma_f32_16x16x32_bf16 v[8:11], v[154:157], v[218:221], 0
	v_mfma_f32_16x16x32_bf16 v[60:63], v[150:153], v[194:197], v[60:63]
	v_mfma_f32_16x16x32_bf16 v[56:59], v[170:173], v[194:197], v[56:59]
	v_mfma_f32_16x16x32_bf16 v[44:47], v[150:153], v[202:205], v[44:47]
	v_mfma_f32_16x16x32_bf16 v[40:43], v[170:173], v[202:205], v[40:43]
	v_mfma_f32_16x16x32_bf16 v[28:31], v[150:153], v[214:217], v[28:31]
	v_mfma_f32_16x16x32_bf16 v[24:27], v[170:173], v[214:217], v[24:27]
	v_mfma_f32_16x16x32_bf16 v[12:15], v[150:153], v[222:225], v[12:15]
	v_mfma_f32_16x16x32_bf16 v[8:11], v[170:173], v[222:225], v[8:11]
	v_mfma_f32_16x16x32_bf16 v[52:55], v[174:177], v[190:193], 0
	v_mfma_f32_16x16x32_bf16 v[48:51], v[182:185], v[190:193], 0
	v_mfma_f32_16x16x32_bf16 v[36:39], v[174:177], v[198:201], 0
	v_mfma_f32_16x16x32_bf16 v[32:35], v[182:185], v[198:201], 0
	v_mfma_f32_16x16x32_bf16 v[20:23], v[174:177], v[206:209], 0
	v_mfma_f32_16x16x32_bf16 v[16:19], v[182:185], v[206:209], 0
	v_mfma_f32_16x16x32_bf16 v[4:7], v[174:177], v[218:221], 0
	v_mfma_f32_16x16x32_bf16 v[0:3], v[182:185], v[218:221], 0
	v_mfma_f32_16x16x32_bf16 v[52:55], v[178:181], v[194:197], v[52:55]
	v_mfma_f32_16x16x32_bf16 v[48:51], v[186:189], v[194:197], v[48:51]
	v_mfma_f32_16x16x32_bf16 v[36:39], v[178:181], v[202:205], v[36:39]
	v_mfma_f32_16x16x32_bf16 v[32:35], v[186:189], v[202:205], v[32:35]
	v_mfma_f32_16x16x32_bf16 v[20:23], v[178:181], v[214:217], v[20:23]
	v_mfma_f32_16x16x32_bf16 v[16:19], v[186:189], v[214:217], v[16:19]
	v_mfma_f32_16x16x32_bf16 v[4:7], v[178:181], v[222:225], v[4:7]
	v_mfma_f32_16x16x32_bf16 v[0:3], v[186:189], v[222:225], v[0:3]
	s_barrier
	s_add_i32 s91, 0, 0x18000
	s_add_i32 s92, 0, 0x1c000
	ds_read_b128 v[146:149], v253
	ds_read_b128 v[150:153], v253 offset:1024
	ds_read_b128 v[154:157], v253 offset:2048
	ds_read_b128 v[170:173], v253 offset:3072
	ds_read_b128 v[174:177], v254
	ds_read_b128 v[178:181], v254 offset:1024
	ds_read_b128 v[182:185], v254 offset:2048
	ds_read_b128 v[186:189], v254 offset:3072
	s_add_u32 s78, s78, 0x80000
	s_addc_u32 s79, s79, 0
	s_mov_b32 m0, s28
	ds_read_b128 v[190:193], v168 offset:32768
	ds_read_b128 v[194:197], v168 offset:33792
	ds_read_b128 v[198:201], v168 offset:34816
	ds_read_b128 v[202:205], v168 offset:35840
	ds_read_b128 v[206:209], v168 offset:36864
	ds_read_b128 v[214:217], v168 offset:37888
	ds_read_b128 v[218:221], v168 offset:38912
	global_load_lds_dwordx4 v128, s[78:79]
	s_mov_b32 m0, s29
	ds_read_b128 v[222:225], v168 offset:39936
	global_load_lds_dwordx4 v132, s[78:79]
	s_waitcnt vmcnt(8) lgkmcnt(0)
	s_barrier
	v_mfma_f32_16x16x32_bf16 v[124:127], v[146:149], v[190:193], v[124:127]
	v_mfma_f32_16x16x32_bf16 v[120:123], v[154:157], v[190:193], v[120:123]
	v_mfma_f32_16x16x32_bf16 v[108:111], v[146:149], v[198:201], v[108:111]
	v_mfma_f32_16x16x32_bf16 v[104:107], v[154:157], v[198:201], v[104:107]
	v_mfma_f32_16x16x32_bf16 v[92:95], v[146:149], v[206:209], v[92:95]
	v_mfma_f32_16x16x32_bf16 v[88:91], v[154:157], v[206:209], v[88:91]
	v_mfma_f32_16x16x32_bf16 v[76:79], v[146:149], v[218:221], v[76:79]
	v_mfma_f32_16x16x32_bf16 v[72:75], v[154:157], v[218:221], v[72:75]
	v_mfma_f32_16x16x32_bf16 v[124:127], v[150:153], v[194:197], v[124:127]
	v_mfma_f32_16x16x32_bf16 v[120:123], v[170:173], v[194:197], v[120:123]
	v_mfma_f32_16x16x32_bf16 v[108:111], v[150:153], v[202:205], v[108:111]
	v_mfma_f32_16x16x32_bf16 v[104:107], v[170:173], v[202:205], v[104:107]
	v_mfma_f32_16x16x32_bf16 v[92:95], v[150:153], v[214:217], v[92:95]
	v_mfma_f32_16x16x32_bf16 v[88:91], v[170:173], v[214:217], v[88:91]
	v_mfma_f32_16x16x32_bf16 v[76:79], v[150:153], v[222:225], v[76:79]
	v_mfma_f32_16x16x32_bf16 v[72:75], v[170:173], v[222:225], v[72:75]
	v_mfma_f32_16x16x32_bf16 v[116:119], v[174:177], v[190:193], v[116:119]
	v_mfma_f32_16x16x32_bf16 v[112:115], v[182:185], v[190:193], v[112:115]
	v_mfma_f32_16x16x32_bf16 v[100:103], v[174:177], v[198:201], v[100:103]
	v_mfma_f32_16x16x32_bf16 v[96:99], v[182:185], v[198:201], v[96:99]
	v_mfma_f32_16x16x32_bf16 v[84:87], v[174:177], v[206:209], v[84:87]
	v_mfma_f32_16x16x32_bf16 v[80:83], v[182:185], v[206:209], v[80:83]
	v_mfma_f32_16x16x32_bf16 v[68:71], v[174:177], v[218:221], v[68:71]
	v_mfma_f32_16x16x32_bf16 v[64:67], v[182:185], v[218:221], v[64:67]
	v_mfma_f32_16x16x32_bf16 v[116:119], v[178:181], v[194:197], v[116:119]
	v_mfma_f32_16x16x32_bf16 v[112:115], v[186:189], v[194:197], v[112:115]
	v_mfma_f32_16x16x32_bf16 v[100:103], v[178:181], v[202:205], v[100:103]
	v_mfma_f32_16x16x32_bf16 v[96:99], v[186:189], v[202:205], v[96:99]
	v_mfma_f32_16x16x32_bf16 v[84:87], v[178:181], v[214:217], v[84:87]
	v_mfma_f32_16x16x32_bf16 v[80:83], v[186:189], v[214:217], v[80:83]
	v_mfma_f32_16x16x32_bf16 v[68:71], v[178:181], v[222:225], v[68:71]
	v_mfma_f32_16x16x32_bf16 v[64:67], v[186:189], v[222:225], v[64:67]
	s_barrier
	s_add_i32 s78, s91, s30
	s_mov_b32 m0, s78
	ds_read_b128 v[190:193], v168 offset:49152
	ds_read_b128 v[194:197], v168 offset:50176
	ds_read_b128 v[198:201], v168 offset:51200
	ds_read_b128 v[202:205], v168 offset:52224
	global_load_lds_dwordx4 v130, s[98:99]
	s_add_i32 m0, s78, 0x2000
	s_add_u32 s76, s76, 0x80080
	s_addc_u32 s77, s77, 0
	s_add_i32 s78, s92, s30
	global_load_lds_dwordx4 v134, s[98:99]
	s_mov_b32 m0, s78
	ds_read_b128 v[222:225], v168 offset:56320
	global_load_lds_dwordx4 v130, s[76:77]
	s_add_i32 m0, s78, 0x2000
	ds_read_b128 v[218:221], v168 offset:55296
	global_load_lds_dwordx4 v134, s[76:77]
	s_mov_b32 m0, s73
	ds_read_b128 v[214:217], v168 offset:54272
	global_load_lds_dwordx4 v128, s[100:101]
	s_mov_b32 m0, s80
	ds_read_b128 v[206:209], v168 offset:53248
	global_load_lds_dwordx4 v132, s[100:101]
	s_waitcnt vmcnt(8) lgkmcnt(0)
	s_barrier
	v_mfma_f32_16x16x32_bf16 v[60:63], v[146:149], v[190:193], v[60:63]
	v_mfma_f32_16x16x32_bf16 v[56:59], v[154:157], v[190:193], v[56:59]
	v_mfma_f32_16x16x32_bf16 v[44:47], v[146:149], v[198:201], v[44:47]
	v_mfma_f32_16x16x32_bf16 v[40:43], v[154:157], v[198:201], v[40:43]
	v_mfma_f32_16x16x32_bf16 v[28:31], v[146:149], v[206:209], v[28:31]
	v_mfma_f32_16x16x32_bf16 v[24:27], v[154:157], v[206:209], v[24:27]
	v_mfma_f32_16x16x32_bf16 v[12:15], v[146:149], v[218:221], v[12:15]
	v_mfma_f32_16x16x32_bf16 v[8:11], v[154:157], v[218:221], v[8:11]
	v_mfma_f32_16x16x32_bf16 v[60:63], v[150:153], v[194:197], v[60:63]
	v_mfma_f32_16x16x32_bf16 v[56:59], v[170:173], v[194:197], v[56:59]
	v_mfma_f32_16x16x32_bf16 v[44:47], v[150:153], v[202:205], v[44:47]
	v_mfma_f32_16x16x32_bf16 v[40:43], v[170:173], v[202:205], v[40:43]
	v_mfma_f32_16x16x32_bf16 v[28:31], v[150:153], v[214:217], v[28:31]
	v_mfma_f32_16x16x32_bf16 v[24:27], v[170:173], v[214:217], v[24:27]
	v_mfma_f32_16x16x32_bf16 v[12:15], v[150:153], v[222:225], v[12:15]
	v_mfma_f32_16x16x32_bf16 v[8:11], v[170:173], v[222:225], v[8:11]
	v_mfma_f32_16x16x32_bf16 v[52:55], v[174:177], v[190:193], v[52:55]
	v_mfma_f32_16x16x32_bf16 v[48:51], v[182:185], v[190:193], v[48:51]
	v_mfma_f32_16x16x32_bf16 v[36:39], v[174:177], v[198:201], v[36:39]
	v_mfma_f32_16x16x32_bf16 v[32:35], v[182:185], v[198:201], v[32:35]
	v_mfma_f32_16x16x32_bf16 v[20:23], v[174:177], v[206:209], v[20:23]
	v_mfma_f32_16x16x32_bf16 v[16:19], v[182:185], v[206:209], v[16:19]
	v_mfma_f32_16x16x32_bf16 v[4:7], v[174:177], v[218:221], v[4:7]
	v_mfma_f32_16x16x32_bf16 v[0:3], v[182:185], v[218:221], v[0:3]
	v_mfma_f32_16x16x32_bf16 v[52:55], v[178:181], v[194:197], v[52:55]
	v_mfma_f32_16x16x32_bf16 v[48:51], v[186:189], v[194:197], v[48:51]
	v_mfma_f32_16x16x32_bf16 v[36:39], v[178:181], v[202:205], v[36:39]
	v_mfma_f32_16x16x32_bf16 v[32:35], v[186:189], v[202:205], v[32:35]
	v_mfma_f32_16x16x32_bf16 v[20:23], v[178:181], v[214:217], v[20:23]
	v_mfma_f32_16x16x32_bf16 v[16:19], v[186:189], v[214:217], v[16:19]
	v_mfma_f32_16x16x32_bf16 v[4:7], v[178:181], v[222:225], v[4:7]
	v_mfma_f32_16x16x32_bf16 v[0:3], v[186:189], v[222:225], v[0:3]
	s_barrier
	s_add_i32 s90, s90, 2
	s_add_u32 s74, s74, 0x100
	s_addc_u32 s75, s75, 0
	s_add_u32 s65, s65, 0x100
	s_addc_u32 s71, s71, 0
	s_cmp_gt_u32 s90, 29
.LBB0_272:
	ds_read_b128 v[146:149], v166
	ds_read_b128 v[150:153], v166 offset:1024
	ds_read_b128 v[154:157], v166 offset:2048
	ds_read_b128 v[170:173], v166 offset:3072
	ds_read_b128 v[174:177], v167
	ds_read_b128 v[178:181], v167 offset:1024
	ds_read_b128 v[182:185], v167 offset:2048
	ds_read_b128 v[186:189], v167 offset:3072
	s_add_u32 s76, s74, 0xfff80080
	s_addc_u32 s77, s75, -1
	s_cmp_eq_u32 s90, 28
	s_cselect_b32 s79, s0, s77
	s_cselect_b32 s78, s1, s76
	s_cselect_b32 s77, s3, s71
	s_cselect_b32 s76, s63, s65
	s_add_i32 m0, s31, 0xc000
	ds_read_b128 v[190:193], v168
	ds_read_b128 v[194:197], v168 offset:1024
	ds_read_b128 v[198:201], v168 offset:2048
	ds_read_b128 v[202:205], v168 offset:3072
	ds_read_b128 v[206:209], v168 offset:4096
	ds_read_b128 v[214:217], v168 offset:5120
	ds_read_b128 v[218:221], v168 offset:6144
	global_load_lds_dwordx4 v138, s[74:75]
	s_add_i32 m0, s31, 0xe000
	ds_read_b128 v[222:225], v168 offset:7168
	global_load_lds_dwordx4 v140, s[74:75]
	s_waitcnt vmcnt(8) lgkmcnt(0)
	s_barrier
	v_mfma_f32_16x16x32_bf16 v[124:127], v[146:149], v[190:193], v[124:127]
	v_mfma_f32_16x16x32_bf16 v[120:123], v[154:157], v[190:193], v[120:123]
	v_mfma_f32_16x16x32_bf16 v[108:111], v[146:149], v[198:201], v[108:111]
	v_mfma_f32_16x16x32_bf16 v[104:107], v[154:157], v[198:201], v[104:107]
	v_mfma_f32_16x16x32_bf16 v[92:95], v[146:149], v[206:209], v[92:95]
	v_mfma_f32_16x16x32_bf16 v[88:91], v[154:157], v[206:209], v[88:91]
	v_mfma_f32_16x16x32_bf16 v[76:79], v[146:149], v[218:221], v[76:79]
	v_mfma_f32_16x16x32_bf16 v[72:75], v[154:157], v[218:221], v[72:75]
	v_mfma_f32_16x16x32_bf16 v[124:127], v[150:153], v[194:197], v[124:127]
	v_mfma_f32_16x16x32_bf16 v[120:123], v[170:173], v[194:197], v[120:123]
	v_mfma_f32_16x16x32_bf16 v[108:111], v[150:153], v[202:205], v[108:111]
	v_mfma_f32_16x16x32_bf16 v[104:107], v[170:173], v[202:205], v[104:107]
	v_mfma_f32_16x16x32_bf16 v[92:95], v[150:153], v[214:217], v[92:95]
	v_mfma_f32_16x16x32_bf16 v[88:91], v[170:173], v[214:217], v[88:91]
	v_mfma_f32_16x16x32_bf16 v[76:79], v[150:153], v[222:225], v[76:79]
	v_mfma_f32_16x16x32_bf16 v[72:75], v[170:173], v[222:225], v[72:75]
	v_mfma_f32_16x16x32_bf16 v[116:119], v[174:177], v[190:193], v[116:119]
	v_mfma_f32_16x16x32_bf16 v[112:115], v[182:185], v[190:193], v[112:115]
	v_mfma_f32_16x16x32_bf16 v[100:103], v[174:177], v[198:201], v[100:103]
	v_mfma_f32_16x16x32_bf16 v[96:99], v[182:185], v[198:201], v[96:99]
	v_mfma_f32_16x16x32_bf16 v[84:87], v[174:177], v[206:209], v[84:87]
	v_mfma_f32_16x16x32_bf16 v[80:83], v[182:185], v[206:209], v[80:83]
	v_mfma_f32_16x16x32_bf16 v[68:71], v[174:177], v[218:221], v[68:71]
	v_mfma_f32_16x16x32_bf16 v[64:67], v[182:185], v[218:221], v[64:67]
	v_mfma_f32_16x16x32_bf16 v[116:119], v[178:181], v[194:197], v[116:119]
	v_mfma_f32_16x16x32_bf16 v[112:115], v[186:189], v[194:197], v[112:115]
	v_mfma_f32_16x16x32_bf16 v[100:103], v[178:181], v[202:205], v[100:103]
	v_mfma_f32_16x16x32_bf16 v[96:99], v[186:189], v[202:205], v[96:99]
	v_mfma_f32_16x16x32_bf16 v[84:87], v[178:181], v[214:217], v[84:87]
	v_mfma_f32_16x16x32_bf16 v[80:83], v[186:189], v[214:217], v[80:83]
	v_mfma_f32_16x16x32_bf16 v[68:71], v[178:181], v[222:225], v[68:71]
	v_mfma_f32_16x16x32_bf16 v[64:67], v[186:189], v[222:225], v[64:67]
	s_barrier
	s_add_i32 s91, s81, s30
	s_add_u32 s98, s76, s34
	s_addc_u32 s99, s77, s35
	s_mov_b32 m0, s91
	ds_read_b128 v[190:193], v168 offset:16384
	ds_read_b128 v[194:197], v168 offset:17408
	ds_read_b128 v[198:201], v168 offset:18432
	ds_read_b128 v[202:205], v168 offset:19456
	ds_read_b128 v[206:209], v168 offset:20480
	global_load_lds_dwordx4 v130, s[76:77]
	s_add_i32 m0, s91, 0x2000
	s_add_u32 s92, s76, 0x80000
	s_addc_u32 s93, s77, 0
	s_add_i32 s91, s83, s30
	global_load_lds_dwordx4 v134, s[76:77]
	s_mov_b32 m0, s91
	s_add_u32 s100, s78, s34
	s_addc_u32 s101, s79, s35
	global_load_lds_dwordx4 v130, s[92:93]
	s_add_i32 m0, s91, 0x2000
	ds_read_b128 v[222:225], v168 offset:23552
	global_load_lds_dwordx4 v134, s[92:93]
	s_mov_b32 m0, s31
	ds_read_b128 v[218:221], v168 offset:22528
	global_load_lds_dwordx4 v128, s[78:79]
	s_mov_b32 m0, s51
	ds_read_b128 v[214:217], v168 offset:21504
	global_load_lds_dwordx4 v132, s[78:79]
	s_waitcnt vmcnt(8) lgkmcnt(0)
	s_barrier
	v_mfma_f32_16x16x32_bf16 v[60:63], v[146:149], v[190:193], v[60:63]
	v_mfma_f32_16x16x32_bf16 v[56:59], v[154:157], v[190:193], v[56:59]
	v_mfma_f32_16x16x32_bf16 v[44:47], v[146:149], v[198:201], v[44:47]
	v_mfma_f32_16x16x32_bf16 v[40:43], v[154:157], v[198:201], v[40:43]
	v_mfma_f32_16x16x32_bf16 v[28:31], v[146:149], v[206:209], v[28:31]
	v_mfma_f32_16x16x32_bf16 v[24:27], v[154:157], v[206:209], v[24:27]
	v_mfma_f32_16x16x32_bf16 v[12:15], v[146:149], v[218:221], v[12:15]
	v_mfma_f32_16x16x32_bf16 v[8:11], v[154:157], v[218:221], v[8:11]
	v_mfma_f32_16x16x32_bf16 v[60:63], v[150:153], v[194:197], v[60:63]
	v_mfma_f32_16x16x32_bf16 v[56:59], v[170:173], v[194:197], v[56:59]
	v_mfma_f32_16x16x32_bf16 v[44:47], v[150:153], v[202:205], v[44:47]
	v_mfma_f32_16x16x32_bf16 v[40:43], v[170:173], v[202:205], v[40:43]
	v_mfma_f32_16x16x32_bf16 v[28:31], v[150:153], v[214:217], v[28:31]
	v_mfma_f32_16x16x32_bf16 v[24:27], v[170:173], v[214:217], v[24:27]
	v_mfma_f32_16x16x32_bf16 v[12:15], v[150:153], v[222:225], v[12:15]
	v_mfma_f32_16x16x32_bf16 v[8:11], v[170:173], v[222:225], v[8:11]
	v_mfma_f32_16x16x32_bf16 v[52:55], v[174:177], v[190:193], v[52:55]
	v_mfma_f32_16x16x32_bf16 v[48:51], v[182:185], v[190:193], v[48:51]
	v_mfma_f32_16x16x32_bf16 v[36:39], v[174:177], v[198:201], v[36:39]
	v_mfma_f32_16x16x32_bf16 v[32:35], v[182:185], v[198:201], v[32:35]
	v_mfma_f32_16x16x32_bf16 v[20:23], v[174:177], v[206:209], v[20:23]
	v_mfma_f32_16x16x32_bf16 v[16:19], v[182:185], v[206:209], v[16:19]
	v_mfma_f32_16x16x32_bf16 v[4:7], v[174:177], v[218:221], v[4:7]
	v_mfma_f32_16x16x32_bf16 v[0:3], v[182:185], v[218:221], v[0:3]
	v_mfma_f32_16x16x32_bf16 v[52:55], v[178:181], v[194:197], v[52:55]
	v_mfma_f32_16x16x32_bf16 v[48:51], v[186:189], v[194:197], v[48:51]
	v_mfma_f32_16x16x32_bf16 v[36:39], v[178:181], v[202:205], v[36:39]
	v_mfma_f32_16x16x32_bf16 v[32:35], v[186:189], v[202:205], v[32:35]
	v_mfma_f32_16x16x32_bf16 v[20:23], v[178:181], v[214:217], v[20:23]
	v_mfma_f32_16x16x32_bf16 v[16:19], v[186:189], v[214:217], v[16:19]
	v_mfma_f32_16x16x32_bf16 v[4:7], v[178:181], v[222:225], v[4:7]
	v_mfma_f32_16x16x32_bf16 v[0:3], v[186:189], v[222:225], v[0:3]
	s_barrier
	s_add_i32 s91, 0, 0x18000
	s_add_i32 s92, 0, 0x1c000
	ds_read_b128 v[146:149], v253
	ds_read_b128 v[150:153], v253 offset:1024
	ds_read_b128 v[154:157], v253 offset:2048
	ds_read_b128 v[170:173], v253 offset:3072
	ds_read_b128 v[174:177], v254
	ds_read_b128 v[178:181], v254 offset:1024
	ds_read_b128 v[182:185], v254 offset:2048
	ds_read_b128 v[186:189], v254 offset:3072
	s_add_u32 s78, s78, 0x80000
	s_addc_u32 s79, s79, 0
	s_mov_b32 m0, s28
	ds_read_b128 v[190:193], v168 offset:32768
	ds_read_b128 v[194:197], v168 offset:33792
	ds_read_b128 v[198:201], v168 offset:34816
	ds_read_b128 v[202:205], v168 offset:35840
	ds_read_b128 v[206:209], v168 offset:36864
	ds_read_b128 v[214:217], v168 offset:37888
	ds_read_b128 v[218:221], v168 offset:38912
	global_load_lds_dwordx4 v128, s[78:79]
	s_mov_b32 m0, s29
	ds_read_b128 v[222:225], v168 offset:39936
	global_load_lds_dwordx4 v132, s[78:79]
	s_waitcnt vmcnt(8) lgkmcnt(0)
	s_barrier
	v_mfma_f32_16x16x32_bf16 v[124:127], v[146:149], v[190:193], v[124:127]
	v_mfma_f32_16x16x32_bf16 v[120:123], v[154:157], v[190:193], v[120:123]
	v_mfma_f32_16x16x32_bf16 v[108:111], v[146:149], v[198:201], v[108:111]
	v_mfma_f32_16x16x32_bf16 v[104:107], v[154:157], v[198:201], v[104:107]
	v_mfma_f32_16x16x32_bf16 v[92:95], v[146:149], v[206:209], v[92:95]
	v_mfma_f32_16x16x32_bf16 v[88:91], v[154:157], v[206:209], v[88:91]
	v_mfma_f32_16x16x32_bf16 v[76:79], v[146:149], v[218:221], v[76:79]
	v_mfma_f32_16x16x32_bf16 v[72:75], v[154:157], v[218:221], v[72:75]
	v_mfma_f32_16x16x32_bf16 v[124:127], v[150:153], v[194:197], v[124:127]
	v_mfma_f32_16x16x32_bf16 v[120:123], v[170:173], v[194:197], v[120:123]
	v_mfma_f32_16x16x32_bf16 v[108:111], v[150:153], v[202:205], v[108:111]
	v_mfma_f32_16x16x32_bf16 v[104:107], v[170:173], v[202:205], v[104:107]
	v_mfma_f32_16x16x32_bf16 v[92:95], v[150:153], v[214:217], v[92:95]
	v_mfma_f32_16x16x32_bf16 v[88:91], v[170:173], v[214:217], v[88:91]
	v_mfma_f32_16x16x32_bf16 v[76:79], v[150:153], v[222:225], v[76:79]
	v_mfma_f32_16x16x32_bf16 v[72:75], v[170:173], v[222:225], v[72:75]
	v_mfma_f32_16x16x32_bf16 v[116:119], v[174:177], v[190:193], v[116:119]
	v_mfma_f32_16x16x32_bf16 v[112:115], v[182:185], v[190:193], v[112:115]
	v_mfma_f32_16x16x32_bf16 v[100:103], v[174:177], v[198:201], v[100:103]
	v_mfma_f32_16x16x32_bf16 v[96:99], v[182:185], v[198:201], v[96:99]
	v_mfma_f32_16x16x32_bf16 v[84:87], v[174:177], v[206:209], v[84:87]
	v_mfma_f32_16x16x32_bf16 v[80:83], v[182:185], v[206:209], v[80:83]
	v_mfma_f32_16x16x32_bf16 v[68:71], v[174:177], v[218:221], v[68:71]
	v_mfma_f32_16x16x32_bf16 v[64:67], v[182:185], v[218:221], v[64:67]
	v_mfma_f32_16x16x32_bf16 v[116:119], v[178:181], v[194:197], v[116:119]
	v_mfma_f32_16x16x32_bf16 v[112:115], v[186:189], v[194:197], v[112:115]
	v_mfma_f32_16x16x32_bf16 v[100:103], v[178:181], v[202:205], v[100:103]
	v_mfma_f32_16x16x32_bf16 v[96:99], v[186:189], v[202:205], v[96:99]
	v_mfma_f32_16x16x32_bf16 v[84:87], v[178:181], v[214:217], v[84:87]
	v_mfma_f32_16x16x32_bf16 v[80:83], v[186:189], v[214:217], v[80:83]
	v_mfma_f32_16x16x32_bf16 v[68:71], v[178:181], v[222:225], v[68:71]
	v_mfma_f32_16x16x32_bf16 v[64:67], v[186:189], v[222:225], v[64:67]
	s_barrier
	s_add_i32 s78, s91, s30
	s_mov_b32 m0, s78
	ds_read_b128 v[190:193], v168 offset:49152
	ds_read_b128 v[194:197], v168 offset:50176
	ds_read_b128 v[198:201], v168 offset:51200
	ds_read_b128 v[202:205], v168 offset:52224
	global_load_lds_dwordx4 v130, s[98:99]
	s_add_i32 m0, s78, 0x2000
	s_add_u32 s76, s76, 0x80080
	s_addc_u32 s77, s77, 0
	s_add_i32 s78, s92, s30
	global_load_lds_dwordx4 v134, s[98:99]
	s_mov_b32 m0, s78
	ds_read_b128 v[222:225], v168 offset:56320
	global_load_lds_dwordx4 v130, s[76:77]
	s_add_i32 m0, s78, 0x2000
	ds_read_b128 v[218:221], v168 offset:55296
	global_load_lds_dwordx4 v134, s[76:77]
	s_mov_b32 m0, s73
	ds_read_b128 v[214:217], v168 offset:54272
	global_load_lds_dwordx4 v128, s[100:101]
	s_mov_b32 m0, s80
	ds_read_b128 v[206:209], v168 offset:53248
	global_load_lds_dwordx4 v132, s[100:101]
	s_waitcnt vmcnt(8) lgkmcnt(0)
	s_barrier
	v_mfma_f32_16x16x32_bf16 v[60:63], v[146:149], v[190:193], v[60:63]
	v_mfma_f32_16x16x32_bf16 v[56:59], v[154:157], v[190:193], v[56:59]
	v_mfma_f32_16x16x32_bf16 v[44:47], v[146:149], v[198:201], v[44:47]
	v_mfma_f32_16x16x32_bf16 v[40:43], v[154:157], v[198:201], v[40:43]
	v_mfma_f32_16x16x32_bf16 v[28:31], v[146:149], v[206:209], v[28:31]
	v_mfma_f32_16x16x32_bf16 v[24:27], v[154:157], v[206:209], v[24:27]
	v_mfma_f32_16x16x32_bf16 v[12:15], v[146:149], v[218:221], v[12:15]
	v_mfma_f32_16x16x32_bf16 v[8:11], v[154:157], v[218:221], v[8:11]
	v_mfma_f32_16x16x32_bf16 v[60:63], v[150:153], v[194:197], v[60:63]
	v_mfma_f32_16x16x32_bf16 v[56:59], v[170:173], v[194:197], v[56:59]
	v_mfma_f32_16x16x32_bf16 v[44:47], v[150:153], v[202:205], v[44:47]
	v_mfma_f32_16x16x32_bf16 v[40:43], v[170:173], v[202:205], v[40:43]
	v_mfma_f32_16x16x32_bf16 v[28:31], v[150:153], v[214:217], v[28:31]
	v_mfma_f32_16x16x32_bf16 v[24:27], v[170:173], v[214:217], v[24:27]
	v_mfma_f32_16x16x32_bf16 v[12:15], v[150:153], v[222:225], v[12:15]
	v_mfma_f32_16x16x32_bf16 v[8:11], v[170:173], v[222:225], v[8:11]
	v_mfma_f32_16x16x32_bf16 v[52:55], v[174:177], v[190:193], v[52:55]
	v_mfma_f32_16x16x32_bf16 v[48:51], v[182:185], v[190:193], v[48:51]
	v_mfma_f32_16x16x32_bf16 v[36:39], v[174:177], v[198:201], v[36:39]
	v_mfma_f32_16x16x32_bf16 v[32:35], v[182:185], v[198:201], v[32:35]
	v_mfma_f32_16x16x32_bf16 v[20:23], v[174:177], v[206:209], v[20:23]
	v_mfma_f32_16x16x32_bf16 v[16:19], v[182:185], v[206:209], v[16:19]
	v_mfma_f32_16x16x32_bf16 v[4:7], v[174:177], v[218:221], v[4:7]
	v_mfma_f32_16x16x32_bf16 v[0:3], v[182:185], v[218:221], v[0:3]
	v_mfma_f32_16x16x32_bf16 v[52:55], v[178:181], v[194:197], v[52:55]
	v_mfma_f32_16x16x32_bf16 v[48:51], v[186:189], v[194:197], v[48:51]
	v_mfma_f32_16x16x32_bf16 v[36:39], v[178:181], v[202:205], v[36:39]
	v_mfma_f32_16x16x32_bf16 v[32:35], v[186:189], v[202:205], v[32:35]
	v_mfma_f32_16x16x32_bf16 v[20:23], v[178:181], v[214:217], v[20:23]
	v_mfma_f32_16x16x32_bf16 v[16:19], v[186:189], v[214:217], v[16:19]
	v_mfma_f32_16x16x32_bf16 v[4:7], v[178:181], v[222:225], v[4:7]
	v_mfma_f32_16x16x32_bf16 v[0:3], v[186:189], v[222:225], v[0:3]
	s_barrier
	s_add_i32 s90, s90, 2
	s_add_u32 s74, s74, 0x100
	s_addc_u32 s75, s75, 0
	s_add_u32 s65, s65, 0x100
	s_addc_u32 s71, s71, 0
	s_cmp_gt_u32 s90, 29
	s_cbranch_scc0 .LBB0_272
	s_and_b64 vcc, exec, s[36:37]
	s_cbranch_vccz .LBB0_275
	s_barrier

.LBB0_542:
	s_ashr_i32 s35, s34, 31
	s_lshl_b64 s[0:1], s[34:35], 20
	s_add_u32 s36, s29, s0
	s_addc_u32 s37, s30, s1
	s_and_b64 s[0:1], s[6:7], exec
	s_cselect_b32 s0, s37, s43
	s_cselect_b32 s1, s36, s42
	s_ashr_i32 s25, s24, 31
	s_lshl_b64 s[38:39], s[24:25], 20
	s_add_u32 s38, s27, s38
	s_addc_u32 s39, s28, s39
	s_and_b64 s[46:47], s[6:7], exec
	s_cselect_b32 s3, s39, s45
	s_cselect_b32 s9, s38, s44
	s_add_u32 s42, s42, 0x80080
	s_addc_u32 s43, s43, 0
	s_add_u32 s25, s44, 0x100
	s_addc_u32 s35, s45, 0
	s_mov_b32 s58, -2
	s_waitcnt lgkmcnt(0)
	s_waitcnt vmcnt(0)
	ds_read_b128 v[128:131], v216
	ds_read_b128 v[132:135], v216 offset:1024
	ds_read_b128 v[136:139], v216 offset:2048
	ds_read_b128 v[140:143], v216 offset:3072
	ds_read_b128 v[144:147], v217
	ds_read_b128 v[148:151], v217 offset:1024
	ds_read_b128 v[152:155], v217 offset:2048
	ds_read_b128 v[156:159], v217 offset:3072
	s_add_u32 s44, s42, 0xfff80080
	s_addc_u32 s45, s43, -1
	s_cmp_eq_u32 s58, 28
	s_cselect_b32 s47, s0, s45
	s_cselect_b32 s46, s1, s44
	s_cselect_b32 s45, s3, s35
	s_cselect_b32 s44, s9, s25
	s_add_i32 m0, s41, 0xc000
	ds_read_b128 v[160:163], v218
	ds_read_b128 v[164:167], v218 offset:1024
	ds_read_b128 v[168:171], v218 offset:2048
	ds_read_b128 v[172:175], v218 offset:3072
	ds_read_b128 v[192:195], v218 offset:4096
	ds_read_b128 v[196:199], v218 offset:5120
	ds_read_b128 v[200:203], v218 offset:6144
	global_load_lds_dwordx4 v184, s[42:43]
	s_add_i32 m0, s41, 0xe000
	ds_read_b128 v[204:207], v218 offset:7168
	global_load_lds_dwordx4 v186, s[42:43]
	s_waitcnt vmcnt(8) lgkmcnt(0)
	s_barrier
	v_mfma_f32_16x16x32_bf16 v[124:127], v[128:131], v[160:163], 0
	v_mfma_f32_16x16x32_bf16 v[120:123], v[136:139], v[160:163], 0
	v_mfma_f32_16x16x32_bf16 v[108:111], v[128:131], v[168:171], 0
	v_mfma_f32_16x16x32_bf16 v[104:107], v[136:139], v[168:171], 0
	v_mfma_f32_16x16x32_bf16 v[92:95], v[128:131], v[192:195], 0
	v_mfma_f32_16x16x32_bf16 v[88:91], v[136:139], v[192:195], 0
	v_mfma_f32_16x16x32_bf16 v[76:79], v[128:131], v[200:203], 0
	v_mfma_f32_16x16x32_bf16 v[72:75], v[136:139], v[200:203], 0
	v_mfma_f32_16x16x32_bf16 v[124:127], v[132:135], v[164:167], v[124:127]
	v_mfma_f32_16x16x32_bf16 v[120:123], v[140:143], v[164:167], v[120:123]
	v_mfma_f32_16x16x32_bf16 v[108:111], v[132:135], v[172:175], v[108:111]
	v_mfma_f32_16x16x32_bf16 v[104:107], v[140:143], v[172:175], v[104:107]
	v_mfma_f32_16x16x32_bf16 v[92:95], v[132:135], v[196:199], v[92:95]
	v_mfma_f32_16x16x32_bf16 v[88:91], v[140:143], v[196:199], v[88:91]
	v_mfma_f32_16x16x32_bf16 v[76:79], v[132:135], v[204:207], v[76:79]
	v_mfma_f32_16x16x32_bf16 v[72:75], v[140:143], v[204:207], v[72:75]
	v_mfma_f32_16x16x32_bf16 v[116:119], v[144:147], v[160:163], 0
	v_mfma_f32_16x16x32_bf16 v[112:115], v[152:155], v[160:163], 0
	v_mfma_f32_16x16x32_bf16 v[100:103], v[144:147], v[168:171], 0
	v_mfma_f32_16x16x32_bf16 v[96:99], v[152:155], v[168:171], 0
	v_mfma_f32_16x16x32_bf16 v[84:87], v[144:147], v[192:195], 0
	v_mfma_f32_16x16x32_bf16 v[80:83], v[152:155], v[192:195], 0
	v_mfma_f32_16x16x32_bf16 v[68:71], v[144:147], v[200:203], 0
	v_mfma_f32_16x16x32_bf16 v[64:67], v[152:155], v[200:203], 0
	v_mfma_f32_16x16x32_bf16 v[116:119], v[148:151], v[164:167], v[116:119]
	v_mfma_f32_16x16x32_bf16 v[112:115], v[156:159], v[164:167], v[112:115]
	v_mfma_f32_16x16x32_bf16 v[100:103], v[148:151], v[172:175], v[100:103]
	v_mfma_f32_16x16x32_bf16 v[96:99], v[156:159], v[172:175], v[96:99]
	v_mfma_f32_16x16x32_bf16 v[84:87], v[148:151], v[196:199], v[84:87]
	v_mfma_f32_16x16x32_bf16 v[80:83], v[156:159], v[196:199], v[80:83]
	v_mfma_f32_16x16x32_bf16 v[68:71], v[148:151], v[204:207], v[68:71]
	v_mfma_f32_16x16x32_bf16 v[64:67], v[156:159], v[204:207], v[64:67]
	s_barrier
	s_add_i32 s59, s55, s31
	s_add_u32 s98, s44, s20
	s_addc_u32 s99, s45, s21
	s_mov_b32 m0, s59
	ds_read_b128 v[160:163], v218 offset:16384
	ds_read_b128 v[164:167], v218 offset:17408
	ds_read_b128 v[168:171], v218 offset:18432
	ds_read_b128 v[172:175], v218 offset:19456
	ds_read_b128 v[192:195], v218 offset:20480
	global_load_lds_dwordx4 v178, s[44:45]
	s_add_i32 m0, s59, 0x2000
	s_add_u32 s60, s44, 0x80000
	s_addc_u32 s61, s45, 0
	s_add_i32 s59, s56, s31
	global_load_lds_dwordx4 v182, s[44:45]
	s_mov_b32 m0, s59
	s_add_u32 s100, s46, s20
	s_addc_u32 s101, s47, s21
	global_load_lds_dwordx4 v178, s[60:61]
	s_add_i32 m0, s59, 0x2000
	ds_read_b128 v[204:207], v218 offset:23552
	global_load_lds_dwordx4 v182, s[60:61]
	s_mov_b32 m0, s41
	ds_read_b128 v[200:203], v218 offset:22528
	global_load_lds_dwordx4 v176, s[46:47]
	s_mov_b32 m0, s48
	ds_read_b128 v[196:199], v218 offset:21504
	global_load_lds_dwordx4 v180, s[46:47]
	s_waitcnt vmcnt(8) lgkmcnt(0)
	s_barrier
	v_mfma_f32_16x16x32_bf16 v[60:63], v[128:131], v[160:163], 0
	v_mfma_f32_16x16x32_bf16 v[56:59], v[136:139], v[160:163], 0
	v_mfma_f32_16x16x32_bf16 v[44:47], v[128:131], v[168:171], 0
	v_mfma_f32_16x16x32_bf16 v[40:43], v[136:139], v[168:171], 0
	v_mfma_f32_16x16x32_bf16 v[28:31], v[128:131], v[192:195], 0
	v_mfma_f32_16x16x32_bf16 v[24:27], v[136:139], v[192:195], 0
	v_mfma_f32_16x16x32_bf16 v[12:15], v[128:131], v[200:203], 0
	v_mfma_f32_16x16x32_bf16 v[8:11], v[136:139], v[200:203], 0
	v_mfma_f32_16x16x32_bf16 v[60:63], v[132:135], v[164:167], v[60:63]
	v_mfma_f32_16x16x32_bf16 v[56:59], v[140:143], v[164:167], v[56:59]
	v_mfma_f32_16x16x32_bf16 v[44:47], v[132:135], v[172:175], v[44:47]
	v_mfma_f32_16x16x32_bf16 v[40:43], v[140:143], v[172:175], v[40:43]
	v_mfma_f32_16x16x32_bf16 v[28:31], v[132:135], v[196:199], v[28:31]
	v_mfma_f32_16x16x32_bf16 v[24:27], v[140:143], v[196:199], v[24:27]
	v_mfma_f32_16x16x32_bf16 v[12:15], v[132:135], v[204:207], v[12:15]
	v_mfma_f32_16x16x32_bf16 v[8:11], v[140:143], v[204:207], v[8:11]
	v_mfma_f32_16x16x32_bf16 v[52:55], v[144:147], v[160:163], 0
	v_mfma_f32_16x16x32_bf16 v[48:51], v[152:155], v[160:163], 0
	v_mfma_f32_16x16x32_bf16 v[36:39], v[144:147], v[168:171], 0
	v_mfma_f32_16x16x32_bf16 v[32:35], v[152:155], v[168:171], 0
	v_mfma_f32_16x16x32_bf16 v[20:23], v[144:147], v[192:195], 0
	v_mfma_f32_16x16x32_bf16 v[16:19], v[152:155], v[192:195], 0
	v_mfma_f32_16x16x32_bf16 v[4:7], v[144:147], v[200:203], 0
	v_mfma_f32_16x16x32_bf16 v[0:3], v[152:155], v[200:203], 0
	v_mfma_f32_16x16x32_bf16 v[52:55], v[148:151], v[164:167], v[52:55]
	v_mfma_f32_16x16x32_bf16 v[48:51], v[156:159], v[164:167], v[48:51]
	v_mfma_f32_16x16x32_bf16 v[36:39], v[148:151], v[172:175], v[36:39]
	v_mfma_f32_16x16x32_bf16 v[32:35], v[156:159], v[172:175], v[32:35]
	v_mfma_f32_16x16x32_bf16 v[20:23], v[148:151], v[196:199], v[20:23]
	v_mfma_f32_16x16x32_bf16 v[16:19], v[156:159], v[196:199], v[16:19]
	v_mfma_f32_16x16x32_bf16 v[4:7], v[148:151], v[204:207], v[4:7]
	v_mfma_f32_16x16x32_bf16 v[0:3], v[156:159], v[204:207], v[0:3]
	s_barrier
	s_add_i32 s59, 0, 0x18000
	s_add_i32 s60, 0, 0x1c000
	ds_read_b128 v[128:131], v253
	ds_read_b128 v[132:135], v253 offset:1024
	ds_read_b128 v[136:139], v253 offset:2048
	ds_read_b128 v[140:143], v253 offset:3072
	ds_read_b128 v[144:147], v254
	ds_read_b128 v[148:151], v254 offset:1024
	ds_read_b128 v[152:155], v254 offset:2048
	ds_read_b128 v[156:159], v254 offset:3072
	s_add_u32 s46, s46, 0x80000
	s_addc_u32 s47, s47, 0
	s_mov_b32 m0, s49
	ds_read_b128 v[160:163], v218 offset:32768
	ds_read_b128 v[164:167], v218 offset:33792
	ds_read_b128 v[168:171], v218 offset:34816
	ds_read_b128 v[172:175], v218 offset:35840
	ds_read_b128 v[192:195], v218 offset:36864
	ds_read_b128 v[196:199], v218 offset:37888
	ds_read_b128 v[200:203], v218 offset:38912
	global_load_lds_dwordx4 v176, s[46:47]
	s_mov_b32 m0, s50
	ds_read_b128 v[204:207], v218 offset:39936
	global_load_lds_dwordx4 v180, s[46:47]
	s_waitcnt vmcnt(8) lgkmcnt(0)
	s_barrier
	v_mfma_f32_16x16x32_bf16 v[124:127], v[128:131], v[160:163], v[124:127]
	v_mfma_f32_16x16x32_bf16 v[120:123], v[136:139], v[160:163], v[120:123]
	v_mfma_f32_16x16x32_bf16 v[108:111], v[128:131], v[168:171], v[108:111]
	v_mfma_f32_16x16x32_bf16 v[104:107], v[136:139], v[168:171], v[104:107]
	v_mfma_f32_16x16x32_bf16 v[92:95], v[128:131], v[192:195], v[92:95]
	v_mfma_f32_16x16x32_bf16 v[88:91], v[136:139], v[192:195], v[88:91]
	v_mfma_f32_16x16x32_bf16 v[76:79], v[128:131], v[200:203], v[76:79]
	v_mfma_f32_16x16x32_bf16 v[72:75], v[136:139], v[200:203], v[72:75]
	v_mfma_f32_16x16x32_bf16 v[124:127], v[132:135], v[164:167], v[124:127]
	v_mfma_f32_16x16x32_bf16 v[120:123], v[140:143], v[164:167], v[120:123]
	v_mfma_f32_16x16x32_bf16 v[108:111], v[132:135], v[172:175], v[108:111]
	v_mfma_f32_16x16x32_bf16 v[104:107], v[140:143], v[172:175], v[104:107]
	v_mfma_f32_16x16x32_bf16 v[92:95], v[132:135], v[196:199], v[92:95]
	v_mfma_f32_16x16x32_bf16 v[88:91], v[140:143], v[196:199], v[88:91]
	v_mfma_f32_16x16x32_bf16 v[76:79], v[132:135], v[204:207], v[76:79]
	v_mfma_f32_16x16x32_bf16 v[72:75], v[140:143], v[204:207], v[72:75]
	v_mfma_f32_16x16x32_bf16 v[116:119], v[144:147], v[160:163], v[116:119]
	v_mfma_f32_16x16x32_bf16 v[112:115], v[152:155], v[160:163], v[112:115]
	v_mfma_f32_16x16x32_bf16 v[100:103], v[144:147], v[168:171], v[100:103]
	v_mfma_f32_16x16x32_bf16 v[96:99], v[152:155], v[168:171], v[96:99]
	v_mfma_f32_16x16x32_bf16 v[84:87], v[144:147], v[192:195], v[84:87]
	v_mfma_f32_16x16x32_bf16 v[80:83], v[152:155], v[192:195], v[80:83]
	v_mfma_f32_16x16x32_bf16 v[68:71], v[144:147], v[200:203], v[68:71]
	v_mfma_f32_16x16x32_bf16 v[64:67], v[152:155], v[200:203], v[64:67]
	v_mfma_f32_16x16x32_bf16 v[116:119], v[148:151], v[164:167], v[116:119]
	v_mfma_f32_16x16x32_bf16 v[112:115], v[156:159], v[164:167], v[112:115]
	v_mfma_f32_16x16x32_bf16 v[100:103], v[148:151], v[172:175], v[100:103]
	v_mfma_f32_16x16x32_bf16 v[96:99], v[156:159], v[172:175], v[96:99]
	v_mfma_f32_16x16x32_bf16 v[84:87], v[148:151], v[196:199], v[84:87]
	v_mfma_f32_16x16x32_bf16 v[80:83], v[156:159], v[196:199], v[80:83]
	v_mfma_f32_16x16x32_bf16 v[68:71], v[148:151], v[204:207], v[68:71]
	v_mfma_f32_16x16x32_bf16 v[64:67], v[156:159], v[204:207], v[64:67]
	s_barrier
	s_add_i32 s46, s59, s31
	s_mov_b32 m0, s46
	ds_read_b128 v[160:163], v218 offset:49152
	ds_read_b128 v[164:167], v218 offset:50176
	ds_read_b128 v[168:171], v218 offset:51200
	ds_read_b128 v[172:175], v218 offset:52224
	global_load_lds_dwordx4 v178, s[98:99]
	s_add_i32 m0, s46, 0x2000
	s_add_u32 s44, s44, 0x80080
	s_addc_u32 s45, s45, 0
	s_add_i32 s46, s60, s31
	global_load_lds_dwordx4 v182, s[98:99]
	s_mov_b32 m0, s46
	ds_read_b128 v[204:207], v218 offset:56320
	global_load_lds_dwordx4 v178, s[44:45]
	s_add_i32 m0, s46, 0x2000
	ds_read_b128 v[200:203], v218 offset:55296
	global_load_lds_dwordx4 v182, s[44:45]
	s_mov_b32 m0, s52
	ds_read_b128 v[196:199], v218 offset:54272
	global_load_lds_dwordx4 v176, s[100:101]
	s_mov_b32 m0, s53
	ds_read_b128 v[192:195], v218 offset:53248
	global_load_lds_dwordx4 v180, s[100:101]
	s_waitcnt vmcnt(8) lgkmcnt(0)
	s_barrier
	v_mfma_f32_16x16x32_bf16 v[60:63], v[128:131], v[160:163], v[60:63]
	v_mfma_f32_16x16x32_bf16 v[56:59], v[136:139], v[160:163], v[56:59]
	v_mfma_f32_16x16x32_bf16 v[44:47], v[128:131], v[168:171], v[44:47]
	v_mfma_f32_16x16x32_bf16 v[40:43], v[136:139], v[168:171], v[40:43]
	v_mfma_f32_16x16x32_bf16 v[28:31], v[128:131], v[192:195], v[28:31]
	v_mfma_f32_16x16x32_bf16 v[24:27], v[136:139], v[192:195], v[24:27]
	v_mfma_f32_16x16x32_bf16 v[12:15], v[128:131], v[200:203], v[12:15]
	v_mfma_f32_16x16x32_bf16 v[8:11], v[136:139], v[200:203], v[8:11]
	v_mfma_f32_16x16x32_bf16 v[60:63], v[132:135], v[164:167], v[60:63]
	v_mfma_f32_16x16x32_bf16 v[56:59], v[140:143], v[164:167], v[56:59]
	v_mfma_f32_16x16x32_bf16 v[44:47], v[132:135], v[172:175], v[44:47]
	v_mfma_f32_16x16x32_bf16 v[40:43], v[140:143], v[172:175], v[40:43]
	v_mfma_f32_16x16x32_bf16 v[28:31], v[132:135], v[196:199], v[28:31]
	v_mfma_f32_16x16x32_bf16 v[24:27], v[140:143], v[196:199], v[24:27]
	v_mfma_f32_16x16x32_bf16 v[12:15], v[132:135], v[204:207], v[12:15]
	v_mfma_f32_16x16x32_bf16 v[8:11], v[140:143], v[204:207], v[8:11]
	v_mfma_f32_16x16x32_bf16 v[52:55], v[144:147], v[160:163], v[52:55]
	v_mfma_f32_16x16x32_bf16 v[48:51], v[152:155], v[160:163], v[48:51]
	v_mfma_f32_16x16x32_bf16 v[36:39], v[144:147], v[168:171], v[36:39]
	v_mfma_f32_16x16x32_bf16 v[32:35], v[152:155], v[168:171], v[32:35]
	v_mfma_f32_16x16x32_bf16 v[20:23], v[144:147], v[192:195], v[20:23]
	v_mfma_f32_16x16x32_bf16 v[16:19], v[152:155], v[192:195], v[16:19]
	v_mfma_f32_16x16x32_bf16 v[4:7], v[144:147], v[200:203], v[4:7]
	v_mfma_f32_16x16x32_bf16 v[0:3], v[152:155], v[200:203], v[0:3]
	v_mfma_f32_16x16x32_bf16 v[52:55], v[148:151], v[164:167], v[52:55]
	v_mfma_f32_16x16x32_bf16 v[48:51], v[156:159], v[164:167], v[48:51]
	v_mfma_f32_16x16x32_bf16 v[36:39], v[148:151], v[172:175], v[36:39]
	v_mfma_f32_16x16x32_bf16 v[32:35], v[156:159], v[172:175], v[32:35]
	v_mfma_f32_16x16x32_bf16 v[20:23], v[148:151], v[196:199], v[20:23]
	v_mfma_f32_16x16x32_bf16 v[16:19], v[156:159], v[196:199], v[16:19]
	v_mfma_f32_16x16x32_bf16 v[4:7], v[148:151], v[204:207], v[4:7]
	v_mfma_f32_16x16x32_bf16 v[0:3], v[156:159], v[204:207], v[0:3]
	s_barrier
	s_add_i32 s58, s58, 2
	s_add_u32 s42, s42, 0x100
	s_addc_u32 s43, s43, 0
	s_add_u32 s25, s25, 0x100
	s_addc_u32 s35, s35, 0
	s_cmp_gt_u32 s58, 29
.LBB0_543:
	ds_read_b128 v[128:131], v216
	ds_read_b128 v[132:135], v216 offset:1024
	ds_read_b128 v[136:139], v216 offset:2048
	ds_read_b128 v[140:143], v216 offset:3072
	ds_read_b128 v[144:147], v217
	ds_read_b128 v[148:151], v217 offset:1024
	ds_read_b128 v[152:155], v217 offset:2048
	ds_read_b128 v[156:159], v217 offset:3072
	s_add_u32 s44, s42, 0xfff80080
	s_addc_u32 s45, s43, -1
	s_cmp_eq_u32 s58, 28
	s_cselect_b32 s47, s0, s45
	s_cselect_b32 s46, s1, s44
	s_cselect_b32 s45, s3, s35
	s_cselect_b32 s44, s9, s25
	s_add_i32 m0, s41, 0xc000
	ds_read_b128 v[160:163], v218
	ds_read_b128 v[164:167], v218 offset:1024
	ds_read_b128 v[168:171], v218 offset:2048
	ds_read_b128 v[172:175], v218 offset:3072
	ds_read_b128 v[192:195], v218 offset:4096
	ds_read_b128 v[196:199], v218 offset:5120
	ds_read_b128 v[200:203], v218 offset:6144
	global_load_lds_dwordx4 v184, s[42:43]
	s_add_i32 m0, s41, 0xe000
	ds_read_b128 v[204:207], v218 offset:7168
	global_load_lds_dwordx4 v186, s[42:43]
	s_waitcnt vmcnt(8) lgkmcnt(0)
	s_barrier
	v_mfma_f32_16x16x32_bf16 v[124:127], v[128:131], v[160:163], v[124:127]
	v_mfma_f32_16x16x32_bf16 v[120:123], v[136:139], v[160:163], v[120:123]
	v_mfma_f32_16x16x32_bf16 v[108:111], v[128:131], v[168:171], v[108:111]
	v_mfma_f32_16x16x32_bf16 v[104:107], v[136:139], v[168:171], v[104:107]
	v_mfma_f32_16x16x32_bf16 v[92:95], v[128:131], v[192:195], v[92:95]
	v_mfma_f32_16x16x32_bf16 v[88:91], v[136:139], v[192:195], v[88:91]
	v_mfma_f32_16x16x32_bf16 v[76:79], v[128:131], v[200:203], v[76:79]
	v_mfma_f32_16x16x32_bf16 v[72:75], v[136:139], v[200:203], v[72:75]
	v_mfma_f32_16x16x32_bf16 v[124:127], v[132:135], v[164:167], v[124:127]
	v_mfma_f32_16x16x32_bf16 v[120:123], v[140:143], v[164:167], v[120:123]
	v_mfma_f32_16x16x32_bf16 v[108:111], v[132:135], v[172:175], v[108:111]
	v_mfma_f32_16x16x32_bf16 v[104:107], v[140:143], v[172:175], v[104:107]
	v_mfma_f32_16x16x32_bf16 v[92:95], v[132:135], v[196:199], v[92:95]
	v_mfma_f32_16x16x32_bf16 v[88:91], v[140:143], v[196:199], v[88:91]
	v_mfma_f32_16x16x32_bf16 v[76:79], v[132:135], v[204:207], v[76:79]
	v_mfma_f32_16x16x32_bf16 v[72:75], v[140:143], v[204:207], v[72:75]
	v_mfma_f32_16x16x32_bf16 v[116:119], v[144:147], v[160:163], v[116:119]
	v_mfma_f32_16x16x32_bf16 v[112:115], v[152:155], v[160:163], v[112:115]
	v_mfma_f32_16x16x32_bf16 v[100:103], v[144:147], v[168:171], v[100:103]
	v_mfma_f32_16x16x32_bf16 v[96:99], v[152:155], v[168:171], v[96:99]
	v_mfma_f32_16x16x32_bf16 v[84:87], v[144:147], v[192:195], v[84:87]
	v_mfma_f32_16x16x32_bf16 v[80:83], v[152:155], v[192:195], v[80:83]
	v_mfma_f32_16x16x32_bf16 v[68:71], v[144:147], v[200:203], v[68:71]
	v_mfma_f32_16x16x32_bf16 v[64:67], v[152:155], v[200:203], v[64:67]
	v_mfma_f32_16x16x32_bf16 v[116:119], v[148:151], v[164:167], v[116:119]
	v_mfma_f32_16x16x32_bf16 v[112:115], v[156:159], v[164:167], v[112:115]
	v_mfma_f32_16x16x32_bf16 v[100:103], v[148:151], v[172:175], v[100:103]
	v_mfma_f32_16x16x32_bf16 v[96:99], v[156:159], v[172:175], v[96:99]
	v_mfma_f32_16x16x32_bf16 v[84:87], v[148:151], v[196:199], v[84:87]
	v_mfma_f32_16x16x32_bf16 v[80:83], v[156:159], v[196:199], v[80:83]
	v_mfma_f32_16x16x32_bf16 v[68:71], v[148:151], v[204:207], v[68:71]
	v_mfma_f32_16x16x32_bf16 v[64:67], v[156:159], v[204:207], v[64:67]
	s_barrier
	s_add_i32 s59, s55, s31
	s_add_u32 s98, s44, s20
	s_addc_u32 s99, s45, s21
	s_mov_b32 m0, s59
	ds_read_b128 v[160:163], v218 offset:16384
	ds_read_b128 v[164:167], v218 offset:17408
	ds_read_b128 v[168:171], v218 offset:18432
	ds_read_b128 v[172:175], v218 offset:19456
	ds_read_b128 v[192:195], v218 offset:20480
	global_load_lds_dwordx4 v178, s[44:45]
	s_add_i32 m0, s59, 0x2000
	s_add_u32 s60, s44, 0x80000
	s_addc_u32 s61, s45, 0
	s_add_i32 s59, s56, s31
	global_load_lds_dwordx4 v182, s[44:45]
	s_mov_b32 m0, s59
	s_add_u32 s100, s46, s20
	s_addc_u32 s101, s47, s21
	global_load_lds_dwordx4 v178, s[60:61]
	s_add_i32 m0, s59, 0x2000
	ds_read_b128 v[204:207], v218 offset:23552
	global_load_lds_dwordx4 v182, s[60:61]
	s_mov_b32 m0, s41
	ds_read_b128 v[200:203], v218 offset:22528
	global_load_lds_dwordx4 v176, s[46:47]
	s_mov_b32 m0, s48
	ds_read_b128 v[196:199], v218 offset:21504
	global_load_lds_dwordx4 v180, s[46:47]
	s_waitcnt vmcnt(8) lgkmcnt(0)
	s_barrier
	v_mfma_f32_16x16x32_bf16 v[60:63], v[128:131], v[160:163], v[60:63]
	v_mfma_f32_16x16x32_bf16 v[56:59], v[136:139], v[160:163], v[56:59]
	v_mfma_f32_16x16x32_bf16 v[44:47], v[128:131], v[168:171], v[44:47]
	v_mfma_f32_16x16x32_bf16 v[40:43], v[136:139], v[168:171], v[40:43]
	v_mfma_f32_16x16x32_bf16 v[28:31], v[128:131], v[192:195], v[28:31]
	v_mfma_f32_16x16x32_bf16 v[24:27], v[136:139], v[192:195], v[24:27]
	v_mfma_f32_16x16x32_bf16 v[12:15], v[128:131], v[200:203], v[12:15]
	v_mfma_f32_16x16x32_bf16 v[8:11], v[136:139], v[200:203], v[8:11]
	v_mfma_f32_16x16x32_bf16 v[60:63], v[132:135], v[164:167], v[60:63]
	v_mfma_f32_16x16x32_bf16 v[56:59], v[140:143], v[164:167], v[56:59]
	v_mfma_f32_16x16x32_bf16 v[44:47], v[132:135], v[172:175], v[44:47]
	v_mfma_f32_16x16x32_bf16 v[40:43], v[140:143], v[172:175], v[40:43]
	v_mfma_f32_16x16x32_bf16 v[28:31], v[132:135], v[196:199], v[28:31]
	v_mfma_f32_16x16x32_bf16 v[24:27], v[140:143], v[196:199], v[24:27]
	v_mfma_f32_16x16x32_bf16 v[12:15], v[132:135], v[204:207], v[12:15]
	v_mfma_f32_16x16x32_bf16 v[8:11], v[140:143], v[204:207], v[8:11]
	v_mfma_f32_16x16x32_bf16 v[52:55], v[144:147], v[160:163], v[52:55]
	v_mfma_f32_16x16x32_bf16 v[48:51], v[152:155], v[160:163], v[48:51]
	v_mfma_f32_16x16x32_bf16 v[36:39], v[144:147], v[168:171], v[36:39]
	v_mfma_f32_16x16x32_bf16 v[32:35], v[152:155], v[168:171], v[32:35]
	v_mfma_f32_16x16x32_bf16 v[20:23], v[144:147], v[192:195], v[20:23]
	v_mfma_f32_16x16x32_bf16 v[16:19], v[152:155], v[192:195], v[16:19]
	v_mfma_f32_16x16x32_bf16 v[4:7], v[144:147], v[200:203], v[4:7]
	v_mfma_f32_16x16x32_bf16 v[0:3], v[152:155], v[200:203], v[0:3]
	v_mfma_f32_16x16x32_bf16 v[52:55], v[148:151], v[164:167], v[52:55]
	v_mfma_f32_16x16x32_bf16 v[48:51], v[156:159], v[164:167], v[48:51]
	v_mfma_f32_16x16x32_bf16 v[36:39], v[148:151], v[172:175], v[36:39]
	v_mfma_f32_16x16x32_bf16 v[32:35], v[156:159], v[172:175], v[32:35]
	v_mfma_f32_16x16x32_bf16 v[20:23], v[148:151], v[196:199], v[20:23]
	v_mfma_f32_16x16x32_bf16 v[16:19], v[156:159], v[196:199], v[16:19]
	v_mfma_f32_16x16x32_bf16 v[4:7], v[148:151], v[204:207], v[4:7]
	v_mfma_f32_16x16x32_bf16 v[0:3], v[156:159], v[204:207], v[0:3]
	s_barrier
	s_add_i32 s59, 0, 0x18000
	s_add_i32 s60, 0, 0x1c000
	ds_read_b128 v[128:131], v253
	ds_read_b128 v[132:135], v253 offset:1024
	ds_read_b128 v[136:139], v253 offset:2048
	ds_read_b128 v[140:143], v253 offset:3072
	ds_read_b128 v[144:147], v254
	ds_read_b128 v[148:151], v254 offset:1024
	ds_read_b128 v[152:155], v254 offset:2048
	ds_read_b128 v[156:159], v254 offset:3072
	s_add_u32 s46, s46, 0x80000
	s_addc_u32 s47, s47, 0
	s_mov_b32 m0, s49
	ds_read_b128 v[160:163], v218 offset:32768
	ds_read_b128 v[164:167], v218 offset:33792
	ds_read_b128 v[168:171], v218 offset:34816
	ds_read_b128 v[172:175], v218 offset:35840
	ds_read_b128 v[192:195], v218 offset:36864
	ds_read_b128 v[196:199], v218 offset:37888
	ds_read_b128 v[200:203], v218 offset:38912
	global_load_lds_dwordx4 v176, s[46:47]
	s_mov_b32 m0, s50
	ds_read_b128 v[204:207], v218 offset:39936
	global_load_lds_dwordx4 v180, s[46:47]
	s_waitcnt vmcnt(8) lgkmcnt(0)
	s_barrier
	v_mfma_f32_16x16x32_bf16 v[124:127], v[128:131], v[160:163], v[124:127]
	v_mfma_f32_16x16x32_bf16 v[120:123], v[136:139], v[160:163], v[120:123]
	v_mfma_f32_16x16x32_bf16 v[108:111], v[128:131], v[168:171], v[108:111]
	v_mfma_f32_16x16x32_bf16 v[104:107], v[136:139], v[168:171], v[104:107]
	v_mfma_f32_16x16x32_bf16 v[92:95], v[128:131], v[192:195], v[92:95]
	v_mfma_f32_16x16x32_bf16 v[88:91], v[136:139], v[192:195], v[88:91]
	v_mfma_f32_16x16x32_bf16 v[76:79], v[128:131], v[200:203], v[76:79]
	v_mfma_f32_16x16x32_bf16 v[72:75], v[136:139], v[200:203], v[72:75]
	v_mfma_f32_16x16x32_bf16 v[124:127], v[132:135], v[164:167], v[124:127]
	v_mfma_f32_16x16x32_bf16 v[120:123], v[140:143], v[164:167], v[120:123]
	v_mfma_f32_16x16x32_bf16 v[108:111], v[132:135], v[172:175], v[108:111]
	v_mfma_f32_16x16x32_bf16 v[104:107], v[140:143], v[172:175], v[104:107]
	v_mfma_f32_16x16x32_bf16 v[92:95], v[132:135], v[196:199], v[92:95]
	v_mfma_f32_16x16x32_bf16 v[88:91], v[140:143], v[196:199], v[88:91]
	v_mfma_f32_16x16x32_bf16 v[76:79], v[132:135], v[204:207], v[76:79]
	v_mfma_f32_16x16x32_bf16 v[72:75], v[140:143], v[204:207], v[72:75]
	v_mfma_f32_16x16x32_bf16 v[116:119], v[144:147], v[160:163], v[116:119]
	v_mfma_f32_16x16x32_bf16 v[112:115], v[152:155], v[160:163], v[112:115]
	v_mfma_f32_16x16x32_bf16 v[100:103], v[144:147], v[168:171], v[100:103]
	v_mfma_f32_16x16x32_bf16 v[96:99], v[152:155], v[168:171], v[96:99]
	v_mfma_f32_16x16x32_bf16 v[84:87], v[144:147], v[192:195], v[84:87]
	v_mfma_f32_16x16x32_bf16 v[80:83], v[152:155], v[192:195], v[80:83]
	v_mfma_f32_16x16x32_bf16 v[68:71], v[144:147], v[200:203], v[68:71]
	v_mfma_f32_16x16x32_bf16 v[64:67], v[152:155], v[200:203], v[64:67]
	v_mfma_f32_16x16x32_bf16 v[116:119], v[148:151], v[164:167], v[116:119]
	v_mfma_f32_16x16x32_bf16 v[112:115], v[156:159], v[164:167], v[112:115]
	v_mfma_f32_16x16x32_bf16 v[100:103], v[148:151], v[172:175], v[100:103]
	v_mfma_f32_16x16x32_bf16 v[96:99], v[156:159], v[172:175], v[96:99]
	v_mfma_f32_16x16x32_bf16 v[84:87], v[148:151], v[196:199], v[84:87]
	v_mfma_f32_16x16x32_bf16 v[80:83], v[156:159], v[196:199], v[80:83]
	v_mfma_f32_16x16x32_bf16 v[68:71], v[148:151], v[204:207], v[68:71]
	v_mfma_f32_16x16x32_bf16 v[64:67], v[156:159], v[204:207], v[64:67]
	s_barrier
	s_add_i32 s46, s59, s31
	s_mov_b32 m0, s46
	ds_read_b128 v[160:163], v218 offset:49152
	ds_read_b128 v[164:167], v218 offset:50176
	ds_read_b128 v[168:171], v218 offset:51200
	ds_read_b128 v[172:175], v218 offset:52224
	global_load_lds_dwordx4 v178, s[98:99]
	s_add_i32 m0, s46, 0x2000
	s_add_u32 s44, s44, 0x80080
	s_addc_u32 s45, s45, 0
	s_add_i32 s46, s60, s31
	global_load_lds_dwordx4 v182, s[98:99]
	s_mov_b32 m0, s46
	ds_read_b128 v[204:207], v218 offset:56320
	global_load_lds_dwordx4 v178, s[44:45]
	s_add_i32 m0, s46, 0x2000
	ds_read_b128 v[200:203], v218 offset:55296
	global_load_lds_dwordx4 v182, s[44:45]
	s_mov_b32 m0, s52
	ds_read_b128 v[196:199], v218 offset:54272
	global_load_lds_dwordx4 v176, s[100:101]
	s_mov_b32 m0, s53
	ds_read_b128 v[192:195], v218 offset:53248
	global_load_lds_dwordx4 v180, s[100:101]
	s_waitcnt vmcnt(8) lgkmcnt(0)
	s_barrier
	v_mfma_f32_16x16x32_bf16 v[60:63], v[128:131], v[160:163], v[60:63]
	v_mfma_f32_16x16x32_bf16 v[56:59], v[136:139], v[160:163], v[56:59]
	v_mfma_f32_16x16x32_bf16 v[44:47], v[128:131], v[168:171], v[44:47]
	v_mfma_f32_16x16x32_bf16 v[40:43], v[136:139], v[168:171], v[40:43]
	v_mfma_f32_16x16x32_bf16 v[28:31], v[128:131], v[192:195], v[28:31]
	v_mfma_f32_16x16x32_bf16 v[24:27], v[136:139], v[192:195], v[24:27]
	v_mfma_f32_16x16x32_bf16 v[12:15], v[128:131], v[200:203], v[12:15]
	v_mfma_f32_16x16x32_bf16 v[8:11], v[136:139], v[200:203], v[8:11]
	v_mfma_f32_16x16x32_bf16 v[60:63], v[132:135], v[164:167], v[60:63]
	v_mfma_f32_16x16x32_bf16 v[56:59], v[140:143], v[164:167], v[56:59]
	v_mfma_f32_16x16x32_bf16 v[44:47], v[132:135], v[172:175], v[44:47]
	v_mfma_f32_16x16x32_bf16 v[40:43], v[140:143], v[172:175], v[40:43]
	v_mfma_f32_16x16x32_bf16 v[28:31], v[132:135], v[196:199], v[28:31]
	v_mfma_f32_16x16x32_bf16 v[24:27], v[140:143], v[196:199], v[24:27]
	v_mfma_f32_16x16x32_bf16 v[12:15], v[132:135], v[204:207], v[12:15]
	v_mfma_f32_16x16x32_bf16 v[8:11], v[140:143], v[204:207], v[8:11]
	v_mfma_f32_16x16x32_bf16 v[52:55], v[144:147], v[160:163], v[52:55]
	v_mfma_f32_16x16x32_bf16 v[48:51], v[152:155], v[160:163], v[48:51]
	v_mfma_f32_16x16x32_bf16 v[36:39], v[144:147], v[168:171], v[36:39]
	v_mfma_f32_16x16x32_bf16 v[32:35], v[152:155], v[168:171], v[32:35]
	v_mfma_f32_16x16x32_bf16 v[20:23], v[144:147], v[192:195], v[20:23]
	v_mfma_f32_16x16x32_bf16 v[16:19], v[152:155], v[192:195], v[16:19]
	v_mfma_f32_16x16x32_bf16 v[4:7], v[144:147], v[200:203], v[4:7]
	v_mfma_f32_16x16x32_bf16 v[0:3], v[152:155], v[200:203], v[0:3]
	v_mfma_f32_16x16x32_bf16 v[52:55], v[148:151], v[164:167], v[52:55]
	v_mfma_f32_16x16x32_bf16 v[48:51], v[156:159], v[164:167], v[48:51]
	v_mfma_f32_16x16x32_bf16 v[36:39], v[148:151], v[172:175], v[36:39]
	v_mfma_f32_16x16x32_bf16 v[32:35], v[156:159], v[172:175], v[32:35]
	v_mfma_f32_16x16x32_bf16 v[20:23], v[148:151], v[196:199], v[20:23]
	v_mfma_f32_16x16x32_bf16 v[16:19], v[156:159], v[196:199], v[16:19]
	v_mfma_f32_16x16x32_bf16 v[4:7], v[148:151], v[204:207], v[4:7]
	v_mfma_f32_16x16x32_bf16 v[0:3], v[156:159], v[204:207], v[0:3]
	s_barrier
	s_add_i32 s58, s58, 2
	s_add_u32 s42, s42, 0x100
	s_addc_u32 s43, s43, 0
	s_add_u32 s25, s25, 0x100
	s_addc_u32 s35, s35, 0
	s_cmp_gt_u32 s58, 29
	s_cbranch_scc0 .LBB0_543
	s_and_b64 vcc, exec, s[22:23]
	s_cbranch_vccz .LBB0_546
	s_barrier

.LBB0_635:
	s_ashr_i32 s67, s66, 31
	s_lshl_b64 s[12:13], s[66:67], 20
	s_add_u32 s70, s55, s12
	s_addc_u32 s71, s57, s13
	s_and_b64 s[6:7], s[6:7], exec
	s_cselect_b32 s1, s71, s11
	s_cselect_b32 s3, s70, s10
	s_add_u32 s6, s8, 0x80080
	s_addc_u32 s7, s9, 0
	s_add_u32 s12, s10, 0x100
	s_addc_u32 s13, s11, 0
	s_mov_b32 s15, -2
	s_waitcnt vmcnt(0)
	ds_read_b128 v[148:151], v197
	ds_read_b128 v[170:173], v197 offset:1024
	ds_read_b128 v[174:177], v197 offset:2048
	ds_read_b128 v[178:181], v197 offset:3072
	ds_read_b128 v[182:185], v198
	ds_read_b128 v[186:189], v198 offset:1024
	ds_read_b128 v[202:205], v198 offset:2048
	ds_read_b128 v[206:209], v198 offset:3072
	s_add_u32 s8, s6, 0xfff80080
	s_addc_u32 s9, s7, -1
	s_cmp_eq_u32 s15, 28
	s_cselect_b32 s11, s69, s9
	s_cselect_b32 s10, s68, s8
	s_cselect_b32 s9, s1, s13
	s_cselect_b32 s8, s3, s12
	s_add_i32 m0, s72, 0xc000
	ds_read_b128 v[214:217], v199
	ds_read_b128 v[218:221], v199 offset:1024
	ds_read_b128 v[222:225], v199 offset:2048
	ds_read_b128 v[226:229], v199 offset:3072
	ds_read_b128 v[230:233], v199 offset:4096
	ds_read_b128 v[234:237], v199 offset:5120
	ds_read_b128 v[238:241], v199 offset:6144
	global_load_lds_dwordx4 v162, s[6:7]
	s_add_i32 m0, s72, 0xe000
	ds_read_b128 v[242:245], v199 offset:7168
	global_load_lds_dwordx4 v164, s[6:7]
	s_waitcnt vmcnt(8) lgkmcnt(0)
	s_barrier
	v_mfma_f32_16x16x32_bf16 v[112:115], v[148:151], v[214:217], 0
	v_mfma_f32_16x16x32_bf16 v[80:83], v[174:177], v[214:217], 0
	v_mfma_f32_16x16x32_bf16 v[116:119], v[148:151], v[222:225], 0
	v_mfma_f32_16x16x32_bf16 v[88:91], v[174:177], v[222:225], 0
	v_mfma_f32_16x16x32_bf16 v[124:127], v[148:151], v[230:233], 0
	v_mfma_f32_16x16x32_bf16 v[92:95], v[174:177], v[230:233], 0
	v_mfma_f32_16x16x32_bf16 v[120:123], v[148:151], v[238:241], 0
	v_mfma_f32_16x16x32_bf16 v[84:87], v[174:177], v[238:241], 0
	v_mfma_f32_16x16x32_bf16 v[112:115], v[170:173], v[218:221], v[112:115]
	v_mfma_f32_16x16x32_bf16 v[80:83], v[178:181], v[218:221], v[80:83]
	v_mfma_f32_16x16x32_bf16 v[116:119], v[170:173], v[226:229], v[116:119]
	v_mfma_f32_16x16x32_bf16 v[88:91], v[178:181], v[226:229], v[88:91]
	v_mfma_f32_16x16x32_bf16 v[124:127], v[170:173], v[234:237], v[124:127]
	v_mfma_f32_16x16x32_bf16 v[92:95], v[178:181], v[234:237], v[92:95]
	v_mfma_f32_16x16x32_bf16 v[120:123], v[170:173], v[242:245], v[120:123]
	v_mfma_f32_16x16x32_bf16 v[84:87], v[178:181], v[242:245], v[84:87]
	v_mfma_f32_16x16x32_bf16 v[108:111], v[182:185], v[214:217], 0
	v_mfma_f32_16x16x32_bf16 v[76:79], v[202:205], v[214:217], 0
	v_mfma_f32_16x16x32_bf16 v[104:107], v[182:185], v[222:225], 0
	v_mfma_f32_16x16x32_bf16 v[72:75], v[202:205], v[222:225], 0
	v_mfma_f32_16x16x32_bf16 v[100:103], v[182:185], v[230:233], 0
	v_mfma_f32_16x16x32_bf16 v[68:71], v[202:205], v[230:233], 0
	v_mfma_f32_16x16x32_bf16 v[96:99], v[182:185], v[238:241], 0
	v_mfma_f32_16x16x32_bf16 v[64:67], v[202:205], v[238:241], 0
	v_mfma_f32_16x16x32_bf16 v[108:111], v[186:189], v[218:221], v[108:111]
	v_mfma_f32_16x16x32_bf16 v[76:79], v[206:209], v[218:221], v[76:79]
	v_mfma_f32_16x16x32_bf16 v[104:107], v[186:189], v[226:229], v[104:107]
	v_mfma_f32_16x16x32_bf16 v[72:75], v[206:209], v[226:229], v[72:75]
	v_mfma_f32_16x16x32_bf16 v[100:103], v[186:189], v[234:237], v[100:103]
	v_mfma_f32_16x16x32_bf16 v[68:71], v[206:209], v[234:237], v[68:71]
	v_mfma_f32_16x16x32_bf16 v[96:99], v[186:189], v[242:245], v[96:99]
	v_mfma_f32_16x16x32_bf16 v[64:67], v[206:209], v[242:245], v[64:67]
	s_barrier
	s_add_i32 s16, s94, s63
	s_add_u32 s98, s8, s40
	s_addc_u32 s99, s9, s41
	s_mov_b32 m0, s16
	ds_read_b128 v[214:217], v199 offset:16384
	ds_read_b128 v[218:221], v199 offset:17408
	ds_read_b128 v[222:225], v199 offset:18432
	ds_read_b128 v[226:229], v199 offset:19456
	ds_read_b128 v[230:233], v199 offset:20480
	global_load_lds_dwordx4 v154, s[8:9]
	s_add_i32 m0, s16, 0x2000
	s_add_u32 s16, s8, 0x80000
	s_addc_u32 s17, s9, 0
	s_add_i32 s18, s95, s63
	global_load_lds_dwordx4 v158, s[8:9]
	s_mov_b32 m0, s18
	s_add_u32 s100, s10, s40
	s_addc_u32 s101, s11, s41
	global_load_lds_dwordx4 v154, s[16:17]
	s_add_i32 m0, s18, 0x2000
	ds_read_b128 v[242:245], v199 offset:23552
	global_load_lds_dwordx4 v158, s[16:17]
	s_mov_b32 m0, s72
	ds_read_b128 v[238:241], v199 offset:22528
	global_load_lds_dwordx4 v152, s[10:11]
	s_mov_b32 m0, s73
	ds_read_b128 v[234:237], v199 offset:21504
	global_load_lds_dwordx4 v156, s[10:11]
	s_waitcnt vmcnt(8) lgkmcnt(0)
	s_barrier
	v_mfma_f32_16x16x32_bf16 v[48:51], v[148:151], v[214:217], 0
	v_mfma_f32_16x16x32_bf16 v[16:19], v[174:177], v[214:217], 0
	v_mfma_f32_16x16x32_bf16 v[52:55], v[148:151], v[222:225], 0
	v_mfma_f32_16x16x32_bf16 v[24:27], v[174:177], v[222:225], 0
	v_mfma_f32_16x16x32_bf16 v[60:63], v[148:151], v[230:233], 0
	v_mfma_f32_16x16x32_bf16 v[28:31], v[174:177], v[230:233], 0
	v_mfma_f32_16x16x32_bf16 v[56:59], v[148:151], v[238:241], 0
	v_mfma_f32_16x16x32_bf16 v[20:23], v[174:177], v[238:241], 0
	v_mfma_f32_16x16x32_bf16 v[48:51], v[170:173], v[218:221], v[48:51]
	v_mfma_f32_16x16x32_bf16 v[16:19], v[178:181], v[218:221], v[16:19]
	v_mfma_f32_16x16x32_bf16 v[52:55], v[170:173], v[226:229], v[52:55]
	v_mfma_f32_16x16x32_bf16 v[24:27], v[178:181], v[226:229], v[24:27]
	v_mfma_f32_16x16x32_bf16 v[60:63], v[170:173], v[234:237], v[60:63]
	v_mfma_f32_16x16x32_bf16 v[28:31], v[178:181], v[234:237], v[28:31]
	v_mfma_f32_16x16x32_bf16 v[56:59], v[170:173], v[242:245], v[56:59]
	v_mfma_f32_16x16x32_bf16 v[20:23], v[178:181], v[242:245], v[20:23]
	v_mfma_f32_16x16x32_bf16 v[44:47], v[182:185], v[214:217], 0
	v_mfma_f32_16x16x32_bf16 v[12:15], v[202:205], v[214:217], 0
	v_mfma_f32_16x16x32_bf16 v[40:43], v[182:185], v[222:225], 0
	v_mfma_f32_16x16x32_bf16 v[8:11], v[202:205], v[222:225], 0
	v_mfma_f32_16x16x32_bf16 v[36:39], v[182:185], v[230:233], 0
	v_mfma_f32_16x16x32_bf16 v[4:7], v[202:205], v[230:233], 0
	v_mfma_f32_16x16x32_bf16 v[32:35], v[182:185], v[238:241], 0
	v_mfma_f32_16x16x32_bf16 v[0:3], v[202:205], v[238:241], 0
	v_mfma_f32_16x16x32_bf16 v[44:47], v[186:189], v[218:221], v[44:47]
	v_mfma_f32_16x16x32_bf16 v[12:15], v[206:209], v[218:221], v[12:15]
	v_mfma_f32_16x16x32_bf16 v[40:43], v[186:189], v[226:229], v[40:43]
	v_mfma_f32_16x16x32_bf16 v[8:11], v[206:209], v[226:229], v[8:11]
	v_mfma_f32_16x16x32_bf16 v[36:39], v[186:189], v[234:237], v[36:39]
	v_mfma_f32_16x16x32_bf16 v[4:7], v[206:209], v[234:237], v[4:7]
	v_mfma_f32_16x16x32_bf16 v[32:35], v[186:189], v[242:245], v[32:35]
	v_mfma_f32_16x16x32_bf16 v[0:3], v[206:209], v[242:245], v[0:3]
	s_barrier
	s_add_i32 s16, 0, 0x18000
	s_add_i32 s17, 0, 0x1c000
	ds_read_b128 v[148:151], v253
	ds_read_b128 v[170:173], v253 offset:1024
	ds_read_b128 v[174:177], v253 offset:2048
	ds_read_b128 v[178:181], v253 offset:3072
	ds_read_b128 v[182:185], v254
	ds_read_b128 v[186:189], v254 offset:1024
	ds_read_b128 v[202:205], v254 offset:2048
	ds_read_b128 v[206:209], v254 offset:3072
	s_add_u32 s10, s10, 0x80000
	s_addc_u32 s11, s11, 0
	s_mov_b32 m0, s74
	ds_read_b128 v[214:217], v199 offset:32768
	ds_read_b128 v[218:221], v199 offset:33792
	ds_read_b128 v[222:225], v199 offset:34816
	ds_read_b128 v[226:229], v199 offset:35840
	ds_read_b128 v[230:233], v199 offset:36864
	ds_read_b128 v[234:237], v199 offset:37888
	ds_read_b128 v[238:241], v199 offset:38912
	global_load_lds_dwordx4 v152, s[10:11]
	s_mov_b32 m0, s75
	ds_read_b128 v[242:245], v199 offset:39936
	global_load_lds_dwordx4 v156, s[10:11]
	s_waitcnt vmcnt(8) lgkmcnt(0)
	s_barrier
	v_mfma_f32_16x16x32_bf16 v[112:115], v[148:151], v[214:217], v[112:115]
	v_mfma_f32_16x16x32_bf16 v[80:83], v[174:177], v[214:217], v[80:83]
	v_mfma_f32_16x16x32_bf16 v[116:119], v[148:151], v[222:225], v[116:119]
	v_mfma_f32_16x16x32_bf16 v[88:91], v[174:177], v[222:225], v[88:91]
	v_mfma_f32_16x16x32_bf16 v[124:127], v[148:151], v[230:233], v[124:127]
	v_mfma_f32_16x16x32_bf16 v[92:95], v[174:177], v[230:233], v[92:95]
	v_mfma_f32_16x16x32_bf16 v[120:123], v[148:151], v[238:241], v[120:123]
	v_mfma_f32_16x16x32_bf16 v[84:87], v[174:177], v[238:241], v[84:87]
	v_mfma_f32_16x16x32_bf16 v[112:115], v[170:173], v[218:221], v[112:115]
	v_mfma_f32_16x16x32_bf16 v[80:83], v[178:181], v[218:221], v[80:83]
	v_mfma_f32_16x16x32_bf16 v[116:119], v[170:173], v[226:229], v[116:119]
	v_mfma_f32_16x16x32_bf16 v[88:91], v[178:181], v[226:229], v[88:91]
	v_mfma_f32_16x16x32_bf16 v[124:127], v[170:173], v[234:237], v[124:127]
	v_mfma_f32_16x16x32_bf16 v[92:95], v[178:181], v[234:237], v[92:95]
	v_mfma_f32_16x16x32_bf16 v[120:123], v[170:173], v[242:245], v[120:123]
	v_mfma_f32_16x16x32_bf16 v[84:87], v[178:181], v[242:245], v[84:87]
	v_mfma_f32_16x16x32_bf16 v[108:111], v[182:185], v[214:217], v[108:111]
	v_mfma_f32_16x16x32_bf16 v[76:79], v[202:205], v[214:217], v[76:79]
	v_mfma_f32_16x16x32_bf16 v[104:107], v[182:185], v[222:225], v[104:107]
	v_mfma_f32_16x16x32_bf16 v[72:75], v[202:205], v[222:225], v[72:75]
	v_mfma_f32_16x16x32_bf16 v[100:103], v[182:185], v[230:233], v[100:103]
	v_mfma_f32_16x16x32_bf16 v[68:71], v[202:205], v[230:233], v[68:71]
	v_mfma_f32_16x16x32_bf16 v[96:99], v[182:185], v[238:241], v[96:99]
	v_mfma_f32_16x16x32_bf16 v[64:67], v[202:205], v[238:241], v[64:67]
	v_mfma_f32_16x16x32_bf16 v[108:111], v[186:189], v[218:221], v[108:111]
	v_mfma_f32_16x16x32_bf16 v[76:79], v[206:209], v[218:221], v[76:79]
	v_mfma_f32_16x16x32_bf16 v[104:107], v[186:189], v[226:229], v[104:107]
	v_mfma_f32_16x16x32_bf16 v[72:75], v[206:209], v[226:229], v[72:75]
	v_mfma_f32_16x16x32_bf16 v[100:103], v[186:189], v[234:237], v[100:103]
	v_mfma_f32_16x16x32_bf16 v[68:71], v[206:209], v[234:237], v[68:71]
	v_mfma_f32_16x16x32_bf16 v[96:99], v[186:189], v[242:245], v[96:99]
	v_mfma_f32_16x16x32_bf16 v[64:67], v[206:209], v[242:245], v[64:67]
	s_barrier
	s_add_i32 s10, s16, s63
	s_mov_b32 m0, s10
	ds_read_b128 v[214:217], v199 offset:49152
	ds_read_b128 v[218:221], v199 offset:50176
	ds_read_b128 v[222:225], v199 offset:51200
	ds_read_b128 v[226:229], v199 offset:52224
	global_load_lds_dwordx4 v154, s[98:99]
	s_add_i32 m0, s10, 0x2000
	s_add_u32 s8, s8, 0x80080
	s_addc_u32 s9, s9, 0
	s_add_i32 s10, s17, s63
	global_load_lds_dwordx4 v158, s[98:99]
	s_mov_b32 m0, s10
	ds_read_b128 v[242:245], v199 offset:56320
	global_load_lds_dwordx4 v154, s[8:9]
	s_add_i32 m0, s10, 0x2000
	ds_read_b128 v[238:241], v199 offset:55296
	global_load_lds_dwordx4 v158, s[8:9]
	s_mov_b32 m0, s82
	ds_read_b128 v[234:237], v199 offset:54272
	global_load_lds_dwordx4 v152, s[100:101]
	s_mov_b32 m0, s83
	ds_read_b128 v[230:233], v199 offset:53248
	global_load_lds_dwordx4 v156, s[100:101]
	s_waitcnt vmcnt(8) lgkmcnt(0)
	s_barrier
	v_mfma_f32_16x16x32_bf16 v[48:51], v[148:151], v[214:217], v[48:51]
	v_mfma_f32_16x16x32_bf16 v[16:19], v[174:177], v[214:217], v[16:19]
	v_mfma_f32_16x16x32_bf16 v[52:55], v[148:151], v[222:225], v[52:55]
	v_mfma_f32_16x16x32_bf16 v[24:27], v[174:177], v[222:225], v[24:27]
	v_mfma_f32_16x16x32_bf16 v[60:63], v[148:151], v[230:233], v[60:63]
	v_mfma_f32_16x16x32_bf16 v[28:31], v[174:177], v[230:233], v[28:31]
	v_mfma_f32_16x16x32_bf16 v[56:59], v[148:151], v[238:241], v[56:59]
	v_mfma_f32_16x16x32_bf16 v[20:23], v[174:177], v[238:241], v[20:23]
	v_mfma_f32_16x16x32_bf16 v[48:51], v[170:173], v[218:221], v[48:51]
	v_mfma_f32_16x16x32_bf16 v[16:19], v[178:181], v[218:221], v[16:19]
	v_mfma_f32_16x16x32_bf16 v[52:55], v[170:173], v[226:229], v[52:55]
	v_mfma_f32_16x16x32_bf16 v[24:27], v[178:181], v[226:229], v[24:27]
	v_mfma_f32_16x16x32_bf16 v[60:63], v[170:173], v[234:237], v[60:63]
	v_mfma_f32_16x16x32_bf16 v[28:31], v[178:181], v[234:237], v[28:31]
	v_mfma_f32_16x16x32_bf16 v[56:59], v[170:173], v[242:245], v[56:59]
	v_mfma_f32_16x16x32_bf16 v[20:23], v[178:181], v[242:245], v[20:23]
	v_mfma_f32_16x16x32_bf16 v[44:47], v[182:185], v[214:217], v[44:47]
	v_mfma_f32_16x16x32_bf16 v[12:15], v[202:205], v[214:217], v[12:15]
	v_mfma_f32_16x16x32_bf16 v[40:43], v[182:185], v[222:225], v[40:43]
	v_mfma_f32_16x16x32_bf16 v[8:11], v[202:205], v[222:225], v[8:11]
	v_mfma_f32_16x16x32_bf16 v[36:39], v[182:185], v[230:233], v[36:39]
	v_mfma_f32_16x16x32_bf16 v[4:7], v[202:205], v[230:233], v[4:7]
	v_mfma_f32_16x16x32_bf16 v[32:35], v[182:185], v[238:241], v[32:35]
	v_mfma_f32_16x16x32_bf16 v[0:3], v[202:205], v[238:241], v[0:3]
	v_mfma_f32_16x16x32_bf16 v[44:47], v[186:189], v[218:221], v[44:47]
	v_mfma_f32_16x16x32_bf16 v[12:15], v[206:209], v[218:221], v[12:15]
	v_mfma_f32_16x16x32_bf16 v[40:43], v[186:189], v[226:229], v[40:43]
	v_mfma_f32_16x16x32_bf16 v[8:11], v[206:209], v[226:229], v[8:11]
	v_mfma_f32_16x16x32_bf16 v[36:39], v[186:189], v[234:237], v[36:39]
	v_mfma_f32_16x16x32_bf16 v[4:7], v[206:209], v[234:237], v[4:7]
	v_mfma_f32_16x16x32_bf16 v[32:35], v[186:189], v[242:245], v[32:35]
	v_mfma_f32_16x16x32_bf16 v[0:3], v[206:209], v[242:245], v[0:3]
	s_barrier
	s_add_i32 s15, s15, 2
	s_add_u32 s6, s6, 0x100
	s_addc_u32 s7, s7, 0
	s_add_u32 s12, s12, 0x100
	s_addc_u32 s13, s13, 0
	s_cmp_gt_u32 s15, 29
.LBB0_636:
	ds_read_b128 v[148:151], v197
	ds_read_b128 v[170:173], v197 offset:1024
	ds_read_b128 v[174:177], v197 offset:2048
	ds_read_b128 v[178:181], v197 offset:3072
	ds_read_b128 v[182:185], v198
	ds_read_b128 v[186:189], v198 offset:1024
	ds_read_b128 v[202:205], v198 offset:2048
	ds_read_b128 v[206:209], v198 offset:3072
	s_add_u32 s8, s6, 0xfff80080
	s_addc_u32 s9, s7, -1
	s_cmp_eq_u32 s15, 28
	s_cselect_b32 s11, s69, s9
	s_cselect_b32 s10, s68, s8
	s_cselect_b32 s9, s1, s13
	s_cselect_b32 s8, s3, s12
	s_add_i32 m0, s72, 0xc000
	ds_read_b128 v[214:217], v199
	ds_read_b128 v[218:221], v199 offset:1024
	ds_read_b128 v[222:225], v199 offset:2048
	ds_read_b128 v[226:229], v199 offset:3072
	ds_read_b128 v[230:233], v199 offset:4096
	ds_read_b128 v[234:237], v199 offset:5120
	ds_read_b128 v[238:241], v199 offset:6144
	global_load_lds_dwordx4 v162, s[6:7]
	s_add_i32 m0, s72, 0xe000
	ds_read_b128 v[242:245], v199 offset:7168
	global_load_lds_dwordx4 v164, s[6:7]
	s_waitcnt vmcnt(8) lgkmcnt(0)
	s_barrier
	v_mfma_f32_16x16x32_bf16 v[112:115], v[148:151], v[214:217], v[112:115]
	v_mfma_f32_16x16x32_bf16 v[80:83], v[174:177], v[214:217], v[80:83]
	v_mfma_f32_16x16x32_bf16 v[116:119], v[148:151], v[222:225], v[116:119]
	v_mfma_f32_16x16x32_bf16 v[88:91], v[174:177], v[222:225], v[88:91]
	v_mfma_f32_16x16x32_bf16 v[124:127], v[148:151], v[230:233], v[124:127]
	v_mfma_f32_16x16x32_bf16 v[92:95], v[174:177], v[230:233], v[92:95]
	v_mfma_f32_16x16x32_bf16 v[120:123], v[148:151], v[238:241], v[120:123]
	v_mfma_f32_16x16x32_bf16 v[84:87], v[174:177], v[238:241], v[84:87]
	v_mfma_f32_16x16x32_bf16 v[112:115], v[170:173], v[218:221], v[112:115]
	v_mfma_f32_16x16x32_bf16 v[80:83], v[178:181], v[218:221], v[80:83]
	v_mfma_f32_16x16x32_bf16 v[116:119], v[170:173], v[226:229], v[116:119]
	v_mfma_f32_16x16x32_bf16 v[88:91], v[178:181], v[226:229], v[88:91]
	v_mfma_f32_16x16x32_bf16 v[124:127], v[170:173], v[234:237], v[124:127]
	v_mfma_f32_16x16x32_bf16 v[92:95], v[178:181], v[234:237], v[92:95]
	v_mfma_f32_16x16x32_bf16 v[120:123], v[170:173], v[242:245], v[120:123]
	v_mfma_f32_16x16x32_bf16 v[84:87], v[178:181], v[242:245], v[84:87]
	v_mfma_f32_16x16x32_bf16 v[108:111], v[182:185], v[214:217], v[108:111]
	v_mfma_f32_16x16x32_bf16 v[76:79], v[202:205], v[214:217], v[76:79]
	v_mfma_f32_16x16x32_bf16 v[104:107], v[182:185], v[222:225], v[104:107]
	v_mfma_f32_16x16x32_bf16 v[72:75], v[202:205], v[222:225], v[72:75]
	v_mfma_f32_16x16x32_bf16 v[100:103], v[182:185], v[230:233], v[100:103]
	v_mfma_f32_16x16x32_bf16 v[68:71], v[202:205], v[230:233], v[68:71]
	v_mfma_f32_16x16x32_bf16 v[96:99], v[182:185], v[238:241], v[96:99]
	v_mfma_f32_16x16x32_bf16 v[64:67], v[202:205], v[238:241], v[64:67]
	v_mfma_f32_16x16x32_bf16 v[108:111], v[186:189], v[218:221], v[108:111]
	v_mfma_f32_16x16x32_bf16 v[76:79], v[206:209], v[218:221], v[76:79]
	v_mfma_f32_16x16x32_bf16 v[104:107], v[186:189], v[226:229], v[104:107]
	v_mfma_f32_16x16x32_bf16 v[72:75], v[206:209], v[226:229], v[72:75]
	v_mfma_f32_16x16x32_bf16 v[100:103], v[186:189], v[234:237], v[100:103]
	v_mfma_f32_16x16x32_bf16 v[68:71], v[206:209], v[234:237], v[68:71]
	v_mfma_f32_16x16x32_bf16 v[96:99], v[186:189], v[242:245], v[96:99]
	v_mfma_f32_16x16x32_bf16 v[64:67], v[206:209], v[242:245], v[64:67]
	s_barrier
	s_add_i32 s16, s94, s63
	s_add_u32 s98, s8, s40
	s_addc_u32 s99, s9, s41
	s_mov_b32 m0, s16
	ds_read_b128 v[214:217], v199 offset:16384
	ds_read_b128 v[218:221], v199 offset:17408
	ds_read_b128 v[222:225], v199 offset:18432
	ds_read_b128 v[226:229], v199 offset:19456
	ds_read_b128 v[230:233], v199 offset:20480
	global_load_lds_dwordx4 v154, s[8:9]
	s_add_i32 m0, s16, 0x2000
	s_add_u32 s16, s8, 0x80000
	s_addc_u32 s17, s9, 0
	s_add_i32 s18, s95, s63
	global_load_lds_dwordx4 v158, s[8:9]
	s_mov_b32 m0, s18
	s_add_u32 s100, s10, s40
	s_addc_u32 s101, s11, s41
	global_load_lds_dwordx4 v154, s[16:17]
	s_add_i32 m0, s18, 0x2000
	ds_read_b128 v[242:245], v199 offset:23552
	global_load_lds_dwordx4 v158, s[16:17]
	s_mov_b32 m0, s72
	ds_read_b128 v[238:241], v199 offset:22528
	global_load_lds_dwordx4 v152, s[10:11]
	s_mov_b32 m0, s73
	ds_read_b128 v[234:237], v199 offset:21504
	global_load_lds_dwordx4 v156, s[10:11]
	s_waitcnt vmcnt(8) lgkmcnt(0)
	s_barrier
	v_mfma_f32_16x16x32_bf16 v[48:51], v[148:151], v[214:217], v[48:51]
	v_mfma_f32_16x16x32_bf16 v[16:19], v[174:177], v[214:217], v[16:19]
	v_mfma_f32_16x16x32_bf16 v[52:55], v[148:151], v[222:225], v[52:55]
	v_mfma_f32_16x16x32_bf16 v[24:27], v[174:177], v[222:225], v[24:27]
	v_mfma_f32_16x16x32_bf16 v[60:63], v[148:151], v[230:233], v[60:63]
	v_mfma_f32_16x16x32_bf16 v[28:31], v[174:177], v[230:233], v[28:31]
	v_mfma_f32_16x16x32_bf16 v[56:59], v[148:151], v[238:241], v[56:59]
	v_mfma_f32_16x16x32_bf16 v[20:23], v[174:177], v[238:241], v[20:23]
	v_mfma_f32_16x16x32_bf16 v[48:51], v[170:173], v[218:221], v[48:51]
	v_mfma_f32_16x16x32_bf16 v[16:19], v[178:181], v[218:221], v[16:19]
	v_mfma_f32_16x16x32_bf16 v[52:55], v[170:173], v[226:229], v[52:55]
	v_mfma_f32_16x16x32_bf16 v[24:27], v[178:181], v[226:229], v[24:27]
	v_mfma_f32_16x16x32_bf16 v[60:63], v[170:173], v[234:237], v[60:63]
	v_mfma_f32_16x16x32_bf16 v[28:31], v[178:181], v[234:237], v[28:31]
	v_mfma_f32_16x16x32_bf16 v[56:59], v[170:173], v[242:245], v[56:59]
	v_mfma_f32_16x16x32_bf16 v[20:23], v[178:181], v[242:245], v[20:23]
	v_mfma_f32_16x16x32_bf16 v[44:47], v[182:185], v[214:217], v[44:47]
	v_mfma_f32_16x16x32_bf16 v[12:15], v[202:205], v[214:217], v[12:15]
	v_mfma_f32_16x16x32_bf16 v[40:43], v[182:185], v[222:225], v[40:43]
	v_mfma_f32_16x16x32_bf16 v[8:11], v[202:205], v[222:225], v[8:11]
	v_mfma_f32_16x16x32_bf16 v[36:39], v[182:185], v[230:233], v[36:39]
	v_mfma_f32_16x16x32_bf16 v[4:7], v[202:205], v[230:233], v[4:7]
	v_mfma_f32_16x16x32_bf16 v[32:35], v[182:185], v[238:241], v[32:35]
	v_mfma_f32_16x16x32_bf16 v[0:3], v[202:205], v[238:241], v[0:3]
	v_mfma_f32_16x16x32_bf16 v[44:47], v[186:189], v[218:221], v[44:47]
	v_mfma_f32_16x16x32_bf16 v[12:15], v[206:209], v[218:221], v[12:15]
	v_mfma_f32_16x16x32_bf16 v[40:43], v[186:189], v[226:229], v[40:43]
	v_mfma_f32_16x16x32_bf16 v[8:11], v[206:209], v[226:229], v[8:11]
	v_mfma_f32_16x16x32_bf16 v[36:39], v[186:189], v[234:237], v[36:39]
	v_mfma_f32_16x16x32_bf16 v[4:7], v[206:209], v[234:237], v[4:7]
	v_mfma_f32_16x16x32_bf16 v[32:35], v[186:189], v[242:245], v[32:35]
	v_mfma_f32_16x16x32_bf16 v[0:3], v[206:209], v[242:245], v[0:3]
	s_barrier
	s_add_i32 s16, 0, 0x18000
	s_add_i32 s17, 0, 0x1c000
	ds_read_b128 v[148:151], v253
	ds_read_b128 v[170:173], v253 offset:1024
	ds_read_b128 v[174:177], v253 offset:2048
	ds_read_b128 v[178:181], v253 offset:3072
	ds_read_b128 v[182:185], v254
	ds_read_b128 v[186:189], v254 offset:1024
	ds_read_b128 v[202:205], v254 offset:2048
	ds_read_b128 v[206:209], v254 offset:3072
	s_add_u32 s10, s10, 0x80000
	s_addc_u32 s11, s11, 0
	s_mov_b32 m0, s74
	ds_read_b128 v[214:217], v199 offset:32768
	ds_read_b128 v[218:221], v199 offset:33792
	ds_read_b128 v[222:225], v199 offset:34816
	ds_read_b128 v[226:229], v199 offset:35840
	ds_read_b128 v[230:233], v199 offset:36864
	ds_read_b128 v[234:237], v199 offset:37888
	ds_read_b128 v[238:241], v199 offset:38912
	global_load_lds_dwordx4 v152, s[10:11]
	s_mov_b32 m0, s75
	ds_read_b128 v[242:245], v199 offset:39936
	global_load_lds_dwordx4 v156, s[10:11]
	s_waitcnt vmcnt(8) lgkmcnt(0)
	s_barrier
	v_mfma_f32_16x16x32_bf16 v[112:115], v[148:151], v[214:217], v[112:115]
	v_mfma_f32_16x16x32_bf16 v[80:83], v[174:177], v[214:217], v[80:83]
	v_mfma_f32_16x16x32_bf16 v[116:119], v[148:151], v[222:225], v[116:119]
	v_mfma_f32_16x16x32_bf16 v[88:91], v[174:177], v[222:225], v[88:91]
	v_mfma_f32_16x16x32_bf16 v[124:127], v[148:151], v[230:233], v[124:127]
	v_mfma_f32_16x16x32_bf16 v[92:95], v[174:177], v[230:233], v[92:95]
	v_mfma_f32_16x16x32_bf16 v[120:123], v[148:151], v[238:241], v[120:123]
	v_mfma_f32_16x16x32_bf16 v[84:87], v[174:177], v[238:241], v[84:87]
	v_mfma_f32_16x16x32_bf16 v[112:115], v[170:173], v[218:221], v[112:115]
	v_mfma_f32_16x16x32_bf16 v[80:83], v[178:181], v[218:221], v[80:83]
	v_mfma_f32_16x16x32_bf16 v[116:119], v[170:173], v[226:229], v[116:119]
	v_mfma_f32_16x16x32_bf16 v[88:91], v[178:181], v[226:229], v[88:91]
	v_mfma_f32_16x16x32_bf16 v[124:127], v[170:173], v[234:237], v[124:127]
	v_mfma_f32_16x16x32_bf16 v[92:95], v[178:181], v[234:237], v[92:95]
	v_mfma_f32_16x16x32_bf16 v[120:123], v[170:173], v[242:245], v[120:123]
	v_mfma_f32_16x16x32_bf16 v[84:87], v[178:181], v[242:245], v[84:87]
	v_mfma_f32_16x16x32_bf16 v[108:111], v[182:185], v[214:217], v[108:111]
	v_mfma_f32_16x16x32_bf16 v[76:79], v[202:205], v[214:217], v[76:79]
	v_mfma_f32_16x16x32_bf16 v[104:107], v[182:185], v[222:225], v[104:107]
	v_mfma_f32_16x16x32_bf16 v[72:75], v[202:205], v[222:225], v[72:75]
	v_mfma_f32_16x16x32_bf16 v[100:103], v[182:185], v[230:233], v[100:103]
	v_mfma_f32_16x16x32_bf16 v[68:71], v[202:205], v[230:233], v[68:71]
	v_mfma_f32_16x16x32_bf16 v[96:99], v[182:185], v[238:241], v[96:99]
	v_mfma_f32_16x16x32_bf16 v[64:67], v[202:205], v[238:241], v[64:67]
	v_mfma_f32_16x16x32_bf16 v[108:111], v[186:189], v[218:221], v[108:111]
	v_mfma_f32_16x16x32_bf16 v[76:79], v[206:209], v[218:221], v[76:79]
	v_mfma_f32_16x16x32_bf16 v[104:107], v[186:189], v[226:229], v[104:107]
	v_mfma_f32_16x16x32_bf16 v[72:75], v[206:209], v[226:229], v[72:75]
	v_mfma_f32_16x16x32_bf16 v[100:103], v[186:189], v[234:237], v[100:103]
	v_mfma_f32_16x16x32_bf16 v[68:71], v[206:209], v[234:237], v[68:71]
	v_mfma_f32_16x16x32_bf16 v[96:99], v[186:189], v[242:245], v[96:99]
	v_mfma_f32_16x16x32_bf16 v[64:67], v[206:209], v[242:245], v[64:67]
	s_barrier
	s_add_i32 s10, s16, s63
	s_mov_b32 m0, s10
	ds_read_b128 v[214:217], v199 offset:49152
	ds_read_b128 v[218:221], v199 offset:50176
	ds_read_b128 v[222:225], v199 offset:51200
	ds_read_b128 v[226:229], v199 offset:52224
	global_load_lds_dwordx4 v154, s[98:99]
	s_add_i32 m0, s10, 0x2000
	s_add_u32 s8, s8, 0x80080
	s_addc_u32 s9, s9, 0
	s_add_i32 s10, s17, s63
	global_load_lds_dwordx4 v158, s[98:99]
	s_mov_b32 m0, s10
	ds_read_b128 v[242:245], v199 offset:56320
	global_load_lds_dwordx4 v154, s[8:9]
	s_add_i32 m0, s10, 0x2000
	ds_read_b128 v[238:241], v199 offset:55296
	global_load_lds_dwordx4 v158, s[8:9]
	s_mov_b32 m0, s82
	ds_read_b128 v[234:237], v199 offset:54272
	global_load_lds_dwordx4 v152, s[100:101]
	s_mov_b32 m0, s83
	ds_read_b128 v[230:233], v199 offset:53248
	global_load_lds_dwordx4 v156, s[100:101]
	s_waitcnt vmcnt(8) lgkmcnt(0)
	s_barrier
	v_mfma_f32_16x16x32_bf16 v[48:51], v[148:151], v[214:217], v[48:51]
	v_mfma_f32_16x16x32_bf16 v[16:19], v[174:177], v[214:217], v[16:19]
	v_mfma_f32_16x16x32_bf16 v[52:55], v[148:151], v[222:225], v[52:55]
	v_mfma_f32_16x16x32_bf16 v[24:27], v[174:177], v[222:225], v[24:27]
	v_mfma_f32_16x16x32_bf16 v[60:63], v[148:151], v[230:233], v[60:63]
	v_mfma_f32_16x16x32_bf16 v[28:31], v[174:177], v[230:233], v[28:31]
	v_mfma_f32_16x16x32_bf16 v[56:59], v[148:151], v[238:241], v[56:59]
	v_mfma_f32_16x16x32_bf16 v[20:23], v[174:177], v[238:241], v[20:23]
	v_mfma_f32_16x16x32_bf16 v[48:51], v[170:173], v[218:221], v[48:51]
	v_mfma_f32_16x16x32_bf16 v[16:19], v[178:181], v[218:221], v[16:19]
	v_mfma_f32_16x16x32_bf16 v[52:55], v[170:173], v[226:229], v[52:55]
	v_mfma_f32_16x16x32_bf16 v[24:27], v[178:181], v[226:229], v[24:27]
	v_mfma_f32_16x16x32_bf16 v[60:63], v[170:173], v[234:237], v[60:63]
	v_mfma_f32_16x16x32_bf16 v[28:31], v[178:181], v[234:237], v[28:31]
	v_mfma_f32_16x16x32_bf16 v[56:59], v[170:173], v[242:245], v[56:59]
	v_mfma_f32_16x16x32_bf16 v[20:23], v[178:181], v[242:245], v[20:23]
	v_mfma_f32_16x16x32_bf16 v[44:47], v[182:185], v[214:217], v[44:47]
	v_mfma_f32_16x16x32_bf16 v[12:15], v[202:205], v[214:217], v[12:15]
	v_mfma_f32_16x16x32_bf16 v[40:43], v[182:185], v[222:225], v[40:43]
	v_mfma_f32_16x16x32_bf16 v[8:11], v[202:205], v[222:225], v[8:11]
	v_mfma_f32_16x16x32_bf16 v[36:39], v[182:185], v[230:233], v[36:39]
	v_mfma_f32_16x16x32_bf16 v[4:7], v[202:205], v[230:233], v[4:7]
	v_mfma_f32_16x16x32_bf16 v[32:35], v[182:185], v[238:241], v[32:35]
	v_mfma_f32_16x16x32_bf16 v[0:3], v[202:205], v[238:241], v[0:3]
	v_mfma_f32_16x16x32_bf16 v[44:47], v[186:189], v[218:221], v[44:47]
	v_mfma_f32_16x16x32_bf16 v[12:15], v[206:209], v[218:221], v[12:15]
	v_mfma_f32_16x16x32_bf16 v[40:43], v[186:189], v[226:229], v[40:43]
	v_mfma_f32_16x16x32_bf16 v[8:11], v[206:209], v[226:229], v[8:11]
	v_mfma_f32_16x16x32_bf16 v[36:39], v[186:189], v[234:237], v[36:39]
	v_mfma_f32_16x16x32_bf16 v[4:7], v[206:209], v[234:237], v[4:7]
	v_mfma_f32_16x16x32_bf16 v[32:35], v[186:189], v[242:245], v[32:35]
	v_mfma_f32_16x16x32_bf16 v[0:3], v[206:209], v[242:245], v[0:3]
	s_barrier
	s_add_i32 s15, s15, 2
	s_add_u32 s6, s6, 0x100
	s_addc_u32 s7, s7, 0
	s_add_u32 s12, s12, 0x100
	s_addc_u32 s13, s13, 0
	s_cmp_gt_u32 s15, 29
	s_cbranch_scc0 .LBB0_636
	s_and_b64 vcc, exec, s[42:43]
	s_cbranch_vccz .LBB0_639
	s_barrier

.LBB0_875:
	s_mov_b32 s1, -2
	s_mov_b64 s[4:5], s[22:23]
	ds_read_b128 v[128:131], v188
	ds_read_b128 v[132:135], v188 offset:1024
	ds_read_b128 v[136:139], v188 offset:2048
	ds_read_b128 v[140:143], v188 offset:3072
	ds_read_b128 v[144:147], v189
	ds_read_b128 v[148:151], v189 offset:1024
	ds_read_b128 v[166:169], v189 offset:2048
	ds_read_b128 v[170:173], v189 offset:3072
	s_add_u32 s40, s38, 0x100
	s_addc_u32 s41, s39, 0
	s_cmpk_eq_i32 s1, 0x52
	s_cselect_b32 s45, s37, s41
	s_cselect_b32 s44, s36, s40
	s_cselect_b32 s43, s17, s5
	s_cselect_b32 s42, s16, s4
	s_add_i32 m0, s48, 0xc000
	ds_read_b128 v[174:177], v190
	ds_read_b128 v[178:181], v190 offset:1024
	ds_read_b128 v[194:197], v190 offset:2048
	ds_read_b128 v[198:201], v190 offset:3072
	ds_read_b128 v[202:205], v190 offset:4096
	ds_read_b128 v[206:209], v190 offset:5120
	ds_read_b128 v[210:213], v190 offset:6144
	global_load_lds_dwordx4 v160, s[38:39]
	s_add_i32 m0, s48, 0xe000
	ds_read_b128 v[214:217], v190 offset:7168
	global_load_lds_dwordx4 v162, s[38:39]
	s_waitcnt vmcnt(8) lgkmcnt(0)
	s_barrier
	v_mfma_f32_16x16x32_bf16 v[124:127], v[128:131], v[174:177], 0
	v_mfma_f32_16x16x32_bf16 v[120:123], v[136:139], v[174:177], 0
	v_mfma_f32_16x16x32_bf16 v[108:111], v[128:131], v[194:197], 0
	v_mfma_f32_16x16x32_bf16 v[104:107], v[136:139], v[194:197], 0
	v_mfma_f32_16x16x32_bf16 v[92:95], v[128:131], v[202:205], 0
	v_mfma_f32_16x16x32_bf16 v[88:91], v[136:139], v[202:205], 0
	v_mfma_f32_16x16x32_bf16 v[76:79], v[128:131], v[210:213], 0
	v_mfma_f32_16x16x32_bf16 v[72:75], v[136:139], v[210:213], 0
	v_mfma_f32_16x16x32_bf16 v[124:127], v[132:135], v[178:181], v[124:127]
	v_mfma_f32_16x16x32_bf16 v[120:123], v[140:143], v[178:181], v[120:123]
	v_mfma_f32_16x16x32_bf16 v[108:111], v[132:135], v[198:201], v[108:111]
	v_mfma_f32_16x16x32_bf16 v[104:107], v[140:143], v[198:201], v[104:107]
	v_mfma_f32_16x16x32_bf16 v[92:95], v[132:135], v[206:209], v[92:95]
	v_mfma_f32_16x16x32_bf16 v[88:91], v[140:143], v[206:209], v[88:91]
	v_mfma_f32_16x16x32_bf16 v[76:79], v[132:135], v[214:217], v[76:79]
	v_mfma_f32_16x16x32_bf16 v[72:75], v[140:143], v[214:217], v[72:75]
	v_mfma_f32_16x16x32_bf16 v[116:119], v[144:147], v[174:177], 0
	v_mfma_f32_16x16x32_bf16 v[112:115], v[166:169], v[174:177], 0
	v_mfma_f32_16x16x32_bf16 v[100:103], v[144:147], v[194:197], 0
	v_mfma_f32_16x16x32_bf16 v[96:99], v[166:169], v[194:197], 0
	v_mfma_f32_16x16x32_bf16 v[84:87], v[144:147], v[202:205], 0
	v_mfma_f32_16x16x32_bf16 v[80:83], v[166:169], v[202:205], 0
	v_mfma_f32_16x16x32_bf16 v[68:71], v[144:147], v[210:213], 0
	v_mfma_f32_16x16x32_bf16 v[64:67], v[166:169], v[210:213], 0
	v_mfma_f32_16x16x32_bf16 v[116:119], v[148:151], v[178:181], v[116:119]
	v_mfma_f32_16x16x32_bf16 v[112:115], v[170:173], v[178:181], v[112:115]
	v_mfma_f32_16x16x32_bf16 v[100:103], v[148:151], v[198:201], v[100:103]
	v_mfma_f32_16x16x32_bf16 v[96:99], v[170:173], v[198:201], v[96:99]
	v_mfma_f32_16x16x32_bf16 v[84:87], v[148:151], v[206:209], v[84:87]
	v_mfma_f32_16x16x32_bf16 v[80:83], v[170:173], v[206:209], v[80:83]
	v_mfma_f32_16x16x32_bf16 v[68:71], v[148:151], v[214:217], v[68:71]
	v_mfma_f32_16x16x32_bf16 v[64:67], v[170:173], v[214:217], v[64:67]
	s_barrier
	s_add_i32 s3, s70, s33
	s_add_u32 s98, s42, s24
	s_addc_u32 s99, s43, s25
	s_mov_b32 m0, s3
	ds_read_b128 v[174:177], v190 offset:16384
	ds_read_b128 v[178:181], v190 offset:17408
	ds_read_b128 v[194:197], v190 offset:18432
	ds_read_b128 v[198:201], v190 offset:19456
	ds_read_b128 v[202:205], v190 offset:20480
	global_load_lds_dwordx4 v154, s[42:43]
	s_add_i32 m0, s3, 0x2000
	s_add_u32 s38, s42, 0x158000
	s_addc_u32 s39, s43, 0
	s_add_i32 s3, s71, s33
	global_load_lds_dwordx4 v158, s[42:43]
	s_mov_b32 m0, s3
	s_add_u32 s100, s44, s24
	s_addc_u32 s101, s45, s25
	global_load_lds_dwordx4 v154, s[38:39]
	s_add_i32 m0, s3, 0x2000
	ds_read_b128 v[214:217], v190 offset:23552
	global_load_lds_dwordx4 v158, s[38:39]
	s_mov_b32 m0, s48
	ds_read_b128 v[210:213], v190 offset:22528
	global_load_lds_dwordx4 v152, s[44:45]
	s_mov_b32 m0, s49
	ds_read_b128 v[206:209], v190 offset:21504
	global_load_lds_dwordx4 v156, s[44:45]
	s_waitcnt vmcnt(8) lgkmcnt(0)
	s_barrier
	v_mfma_f32_16x16x32_bf16 v[60:63], v[128:131], v[174:177], 0
	v_mfma_f32_16x16x32_bf16 v[56:59], v[136:139], v[174:177], 0
	v_mfma_f32_16x16x32_bf16 v[44:47], v[128:131], v[194:197], 0
	v_mfma_f32_16x16x32_bf16 v[40:43], v[136:139], v[194:197], 0
	v_mfma_f32_16x16x32_bf16 v[28:31], v[128:131], v[202:205], 0
	v_mfma_f32_16x16x32_bf16 v[24:27], v[136:139], v[202:205], 0
	v_mfma_f32_16x16x32_bf16 v[12:15], v[128:131], v[210:213], 0
	v_mfma_f32_16x16x32_bf16 v[8:11], v[136:139], v[210:213], 0
	v_mfma_f32_16x16x32_bf16 v[60:63], v[132:135], v[178:181], v[60:63]
	v_mfma_f32_16x16x32_bf16 v[56:59], v[140:143], v[178:181], v[56:59]
	v_mfma_f32_16x16x32_bf16 v[44:47], v[132:135], v[198:201], v[44:47]
	v_mfma_f32_16x16x32_bf16 v[40:43], v[140:143], v[198:201], v[40:43]
	v_mfma_f32_16x16x32_bf16 v[28:31], v[132:135], v[206:209], v[28:31]
	v_mfma_f32_16x16x32_bf16 v[24:27], v[140:143], v[206:209], v[24:27]
	v_mfma_f32_16x16x32_bf16 v[12:15], v[132:135], v[214:217], v[12:15]
	v_mfma_f32_16x16x32_bf16 v[8:11], v[140:143], v[214:217], v[8:11]
	v_mfma_f32_16x16x32_bf16 v[52:55], v[144:147], v[174:177], 0
	v_mfma_f32_16x16x32_bf16 v[48:51], v[166:169], v[174:177], 0
	v_mfma_f32_16x16x32_bf16 v[36:39], v[144:147], v[194:197], 0
	v_mfma_f32_16x16x32_bf16 v[32:35], v[166:169], v[194:197], 0
	v_mfma_f32_16x16x32_bf16 v[20:23], v[144:147], v[202:205], 0
	v_mfma_f32_16x16x32_bf16 v[16:19], v[166:169], v[202:205], 0
	v_mfma_f32_16x16x32_bf16 v[4:7], v[144:147], v[210:213], 0
	v_mfma_f32_16x16x32_bf16 v[0:3], v[166:169], v[210:213], 0
	v_mfma_f32_16x16x32_bf16 v[52:55], v[148:151], v[178:181], v[52:55]
	v_mfma_f32_16x16x32_bf16 v[48:51], v[170:173], v[178:181], v[48:51]
	v_mfma_f32_16x16x32_bf16 v[36:39], v[148:151], v[198:201], v[36:39]
	v_mfma_f32_16x16x32_bf16 v[32:35], v[170:173], v[198:201], v[32:35]
	v_mfma_f32_16x16x32_bf16 v[20:23], v[148:151], v[206:209], v[20:23]
	v_mfma_f32_16x16x32_bf16 v[16:19], v[170:173], v[206:209], v[16:19]
	v_mfma_f32_16x16x32_bf16 v[4:7], v[148:151], v[214:217], v[4:7]
	v_mfma_f32_16x16x32_bf16 v[0:3], v[170:173], v[214:217], v[0:3]
	s_barrier
	s_add_i32 s3, 0, 0x18000
	s_add_i32 s73, 0, 0x1c000
	v_add_u32_e32 v140, s3, v187
	v_add_u32_e32 v170, s73, v187
	ds_read_b128 v[128:131], v140
	ds_read_b128 v[132:135], v140 offset:1024
	ds_read_b128 v[136:139], v140 offset:2048
	ds_read_b128 v[140:143], v140 offset:3072
	ds_read_b128 v[144:147], v170
	ds_read_b128 v[148:151], v170 offset:1024
	ds_read_b128 v[166:169], v170 offset:2048
	ds_read_b128 v[170:173], v170 offset:3072
	s_add_u32 s38, s44, 0x158000
	s_addc_u32 s39, s45, 0
	s_mov_b32 m0, s51
	ds_read_b128 v[174:177], v190 offset:32768
	ds_read_b128 v[178:181], v190 offset:33792
	ds_read_b128 v[194:197], v190 offset:34816
	ds_read_b128 v[198:201], v190 offset:35840
	ds_read_b128 v[202:205], v190 offset:36864
	ds_read_b128 v[206:209], v190 offset:37888
	ds_read_b128 v[210:213], v190 offset:38912
	global_load_lds_dwordx4 v152, s[38:39]
	s_mov_b32 m0, s52
	ds_read_b128 v[214:217], v190 offset:39936
	global_load_lds_dwordx4 v156, s[38:39]
	s_waitcnt vmcnt(8) lgkmcnt(0)
	s_barrier
	v_mfma_f32_16x16x32_bf16 v[124:127], v[128:131], v[174:177], v[124:127]
	v_mfma_f32_16x16x32_bf16 v[120:123], v[136:139], v[174:177], v[120:123]
	v_mfma_f32_16x16x32_bf16 v[108:111], v[128:131], v[194:197], v[108:111]
	v_mfma_f32_16x16x32_bf16 v[104:107], v[136:139], v[194:197], v[104:107]
	v_mfma_f32_16x16x32_bf16 v[92:95], v[128:131], v[202:205], v[92:95]
	v_mfma_f32_16x16x32_bf16 v[88:91], v[136:139], v[202:205], v[88:91]
	v_mfma_f32_16x16x32_bf16 v[76:79], v[128:131], v[210:213], v[76:79]
	v_mfma_f32_16x16x32_bf16 v[72:75], v[136:139], v[210:213], v[72:75]
	v_mfma_f32_16x16x32_bf16 v[124:127], v[132:135], v[178:181], v[124:127]
	v_mfma_f32_16x16x32_bf16 v[120:123], v[140:143], v[178:181], v[120:123]
	v_mfma_f32_16x16x32_bf16 v[108:111], v[132:135], v[198:201], v[108:111]
	v_mfma_f32_16x16x32_bf16 v[104:107], v[140:143], v[198:201], v[104:107]
	v_mfma_f32_16x16x32_bf16 v[92:95], v[132:135], v[206:209], v[92:95]
	v_mfma_f32_16x16x32_bf16 v[88:91], v[140:143], v[206:209], v[88:91]
	v_mfma_f32_16x16x32_bf16 v[76:79], v[132:135], v[214:217], v[76:79]
	v_mfma_f32_16x16x32_bf16 v[72:75], v[140:143], v[214:217], v[72:75]
	v_mfma_f32_16x16x32_bf16 v[116:119], v[144:147], v[174:177], v[116:119]
	v_mfma_f32_16x16x32_bf16 v[112:115], v[166:169], v[174:177], v[112:115]
	v_mfma_f32_16x16x32_bf16 v[100:103], v[144:147], v[194:197], v[100:103]
	v_mfma_f32_16x16x32_bf16 v[96:99], v[166:169], v[194:197], v[96:99]
	v_mfma_f32_16x16x32_bf16 v[84:87], v[144:147], v[202:205], v[84:87]
	v_mfma_f32_16x16x32_bf16 v[80:83], v[166:169], v[202:205], v[80:83]
	v_mfma_f32_16x16x32_bf16 v[68:71], v[144:147], v[210:213], v[68:71]
	v_mfma_f32_16x16x32_bf16 v[64:67], v[166:169], v[210:213], v[64:67]
	v_mfma_f32_16x16x32_bf16 v[116:119], v[148:151], v[178:181], v[116:119]
	v_mfma_f32_16x16x32_bf16 v[112:115], v[170:173], v[178:181], v[112:115]
	v_mfma_f32_16x16x32_bf16 v[100:103], v[148:151], v[198:201], v[100:103]
	v_mfma_f32_16x16x32_bf16 v[96:99], v[170:173], v[198:201], v[96:99]
	v_mfma_f32_16x16x32_bf16 v[84:87], v[148:151], v[206:209], v[84:87]
	v_mfma_f32_16x16x32_bf16 v[80:83], v[170:173], v[206:209], v[80:83]
	v_mfma_f32_16x16x32_bf16 v[68:71], v[148:151], v[214:217], v[68:71]
	v_mfma_f32_16x16x32_bf16 v[64:67], v[170:173], v[214:217], v[64:67]
	s_barrier
	s_add_i32 s3, s3, s33
	s_mov_b32 m0, s3
	ds_read_b128 v[174:177], v190 offset:49152
	ds_read_b128 v[178:181], v190 offset:50176
	ds_read_b128 v[194:197], v190 offset:51200
	ds_read_b128 v[198:201], v190 offset:52224
	global_load_lds_dwordx4 v154, s[98:99]
	s_add_i32 m0, s3, 0x2000
	s_add_u32 s38, s42, 0x158080
	s_addc_u32 s39, s43, 0
	s_add_i32 s3, s73, s33
	global_load_lds_dwordx4 v158, s[98:99]
	s_mov_b32 m0, s3
	ds_read_b128 v[214:217], v190 offset:56320
	global_load_lds_dwordx4 v154, s[38:39]
	s_add_i32 m0, s3, 0x2000
	ds_read_b128 v[210:213], v190 offset:55296
	global_load_lds_dwordx4 v158, s[38:39]
	s_mov_b32 m0, s56
	ds_read_b128 v[206:209], v190 offset:54272
	global_load_lds_dwordx4 v152, s[100:101]
	s_mov_b32 m0, s57
	ds_read_b128 v[202:205], v190 offset:53248
	global_load_lds_dwordx4 v156, s[100:101]
	s_waitcnt vmcnt(8) lgkmcnt(0)
	s_barrier
	v_mfma_f32_16x16x32_bf16 v[60:63], v[128:131], v[174:177], v[60:63]
	v_mfma_f32_16x16x32_bf16 v[56:59], v[136:139], v[174:177], v[56:59]
	v_mfma_f32_16x16x32_bf16 v[44:47], v[128:131], v[194:197], v[44:47]
	v_mfma_f32_16x16x32_bf16 v[40:43], v[136:139], v[194:197], v[40:43]
	v_mfma_f32_16x16x32_bf16 v[28:31], v[128:131], v[202:205], v[28:31]
	v_mfma_f32_16x16x32_bf16 v[24:27], v[136:139], v[202:205], v[24:27]
	v_mfma_f32_16x16x32_bf16 v[12:15], v[128:131], v[210:213], v[12:15]
	v_mfma_f32_16x16x32_bf16 v[8:11], v[136:139], v[210:213], v[8:11]
	v_mfma_f32_16x16x32_bf16 v[60:63], v[132:135], v[178:181], v[60:63]
	v_mfma_f32_16x16x32_bf16 v[56:59], v[140:143], v[178:181], v[56:59]
	v_mfma_f32_16x16x32_bf16 v[44:47], v[132:135], v[198:201], v[44:47]
	v_mfma_f32_16x16x32_bf16 v[40:43], v[140:143], v[198:201], v[40:43]
	v_mfma_f32_16x16x32_bf16 v[28:31], v[132:135], v[206:209], v[28:31]
	v_mfma_f32_16x16x32_bf16 v[24:27], v[140:143], v[206:209], v[24:27]
	v_mfma_f32_16x16x32_bf16 v[12:15], v[132:135], v[214:217], v[12:15]
	v_mfma_f32_16x16x32_bf16 v[8:11], v[140:143], v[214:217], v[8:11]
	v_mfma_f32_16x16x32_bf16 v[52:55], v[144:147], v[174:177], v[52:55]
	v_mfma_f32_16x16x32_bf16 v[48:51], v[166:169], v[174:177], v[48:51]
	v_mfma_f32_16x16x32_bf16 v[36:39], v[144:147], v[194:197], v[36:39]
	v_mfma_f32_16x16x32_bf16 v[32:35], v[166:169], v[194:197], v[32:35]
	v_mfma_f32_16x16x32_bf16 v[20:23], v[144:147], v[202:205], v[20:23]
	v_mfma_f32_16x16x32_bf16 v[16:19], v[166:169], v[202:205], v[16:19]
	v_mfma_f32_16x16x32_bf16 v[4:7], v[144:147], v[210:213], v[4:7]
	v_mfma_f32_16x16x32_bf16 v[0:3], v[166:169], v[210:213], v[0:3]
	v_mfma_f32_16x16x32_bf16 v[52:55], v[148:151], v[178:181], v[52:55]
	v_mfma_f32_16x16x32_bf16 v[48:51], v[170:173], v[178:181], v[48:51]
	v_mfma_f32_16x16x32_bf16 v[36:39], v[148:151], v[198:201], v[36:39]
	v_mfma_f32_16x16x32_bf16 v[32:35], v[170:173], v[198:201], v[32:35]
	v_mfma_f32_16x16x32_bf16 v[20:23], v[148:151], v[206:209], v[20:23]
	v_mfma_f32_16x16x32_bf16 v[16:19], v[170:173], v[206:209], v[16:19]
	v_mfma_f32_16x16x32_bf16 v[4:7], v[148:151], v[214:217], v[4:7]
	v_mfma_f32_16x16x32_bf16 v[0:3], v[170:173], v[214:217], v[0:3]
	s_barrier
	s_add_i32 s1, s1, 2
	s_add_u32 s4, s4, 0x100
	s_addc_u32 s5, s5, 0
	s_cmpk_gt_u32 s1, 0x53
	s_mov_b64 s[38:39], s[40:41]
.LBB0_876:
	ds_read_b128 v[128:131], v188
	ds_read_b128 v[132:135], v188 offset:1024
	ds_read_b128 v[136:139], v188 offset:2048
	ds_read_b128 v[140:143], v188 offset:3072
	ds_read_b128 v[144:147], v189
	ds_read_b128 v[148:151], v189 offset:1024
	ds_read_b128 v[166:169], v189 offset:2048
	ds_read_b128 v[170:173], v189 offset:3072
	s_add_u32 s40, s38, 0x100
	s_addc_u32 s41, s39, 0
	s_cmpk_eq_i32 s1, 0x52
	s_cselect_b32 s45, s37, s41
	s_cselect_b32 s44, s36, s40
	s_cselect_b32 s43, s17, s5
	s_cselect_b32 s42, s16, s4
	s_add_i32 m0, s48, 0xc000
	ds_read_b128 v[174:177], v190
	ds_read_b128 v[178:181], v190 offset:1024
	ds_read_b128 v[194:197], v190 offset:2048
	ds_read_b128 v[198:201], v190 offset:3072
	ds_read_b128 v[202:205], v190 offset:4096
	ds_read_b128 v[206:209], v190 offset:5120
	ds_read_b128 v[210:213], v190 offset:6144
	global_load_lds_dwordx4 v160, s[38:39]
	s_add_i32 m0, s48, 0xe000
	ds_read_b128 v[214:217], v190 offset:7168
	global_load_lds_dwordx4 v162, s[38:39]
	s_waitcnt vmcnt(8) lgkmcnt(0)
	s_barrier
	v_mfma_f32_16x16x32_bf16 v[124:127], v[128:131], v[174:177], v[124:127]
	v_mfma_f32_16x16x32_bf16 v[120:123], v[136:139], v[174:177], v[120:123]
	v_mfma_f32_16x16x32_bf16 v[108:111], v[128:131], v[194:197], v[108:111]
	v_mfma_f32_16x16x32_bf16 v[104:107], v[136:139], v[194:197], v[104:107]
	v_mfma_f32_16x16x32_bf16 v[92:95], v[128:131], v[202:205], v[92:95]
	v_mfma_f32_16x16x32_bf16 v[88:91], v[136:139], v[202:205], v[88:91]
	v_mfma_f32_16x16x32_bf16 v[76:79], v[128:131], v[210:213], v[76:79]
	v_mfma_f32_16x16x32_bf16 v[72:75], v[136:139], v[210:213], v[72:75]
	v_mfma_f32_16x16x32_bf16 v[124:127], v[132:135], v[178:181], v[124:127]
	v_mfma_f32_16x16x32_bf16 v[120:123], v[140:143], v[178:181], v[120:123]
	v_mfma_f32_16x16x32_bf16 v[108:111], v[132:135], v[198:201], v[108:111]
	v_mfma_f32_16x16x32_bf16 v[104:107], v[140:143], v[198:201], v[104:107]
	v_mfma_f32_16x16x32_bf16 v[92:95], v[132:135], v[206:209], v[92:95]
	v_mfma_f32_16x16x32_bf16 v[88:91], v[140:143], v[206:209], v[88:91]
	v_mfma_f32_16x16x32_bf16 v[76:79], v[132:135], v[214:217], v[76:79]
	v_mfma_f32_16x16x32_bf16 v[72:75], v[140:143], v[214:217], v[72:75]
	v_mfma_f32_16x16x32_bf16 v[116:119], v[144:147], v[174:177], v[116:119]
	v_mfma_f32_16x16x32_bf16 v[112:115], v[166:169], v[174:177], v[112:115]
	v_mfma_f32_16x16x32_bf16 v[100:103], v[144:147], v[194:197], v[100:103]
	v_mfma_f32_16x16x32_bf16 v[96:99], v[166:169], v[194:197], v[96:99]
	v_mfma_f32_16x16x32_bf16 v[84:87], v[144:147], v[202:205], v[84:87]
	v_mfma_f32_16x16x32_bf16 v[80:83], v[166:169], v[202:205], v[80:83]
	v_mfma_f32_16x16x32_bf16 v[68:71], v[144:147], v[210:213], v[68:71]
	v_mfma_f32_16x16x32_bf16 v[64:67], v[166:169], v[210:213], v[64:67]
	v_mfma_f32_16x16x32_bf16 v[116:119], v[148:151], v[178:181], v[116:119]
	v_mfma_f32_16x16x32_bf16 v[112:115], v[170:173], v[178:181], v[112:115]
	v_mfma_f32_16x16x32_bf16 v[100:103], v[148:151], v[198:201], v[100:103]
	v_mfma_f32_16x16x32_bf16 v[96:99], v[170:173], v[198:201], v[96:99]
	v_mfma_f32_16x16x32_bf16 v[84:87], v[148:151], v[206:209], v[84:87]
	v_mfma_f32_16x16x32_bf16 v[80:83], v[170:173], v[206:209], v[80:83]
	v_mfma_f32_16x16x32_bf16 v[68:71], v[148:151], v[214:217], v[68:71]
	v_mfma_f32_16x16x32_bf16 v[64:67], v[170:173], v[214:217], v[64:67]
	s_barrier
	s_add_i32 s3, s70, s33
	s_add_u32 s98, s42, s24
	s_addc_u32 s99, s43, s25
	s_mov_b32 m0, s3
	ds_read_b128 v[174:177], v190 offset:16384
	ds_read_b128 v[178:181], v190 offset:17408
	ds_read_b128 v[194:197], v190 offset:18432
	ds_read_b128 v[198:201], v190 offset:19456
	ds_read_b128 v[202:205], v190 offset:20480
	global_load_lds_dwordx4 v154, s[42:43]
	s_add_i32 m0, s3, 0x2000
	s_add_u32 s38, s42, 0x158000
	s_addc_u32 s39, s43, 0
	s_add_i32 s3, s71, s33
	global_load_lds_dwordx4 v158, s[42:43]
	s_mov_b32 m0, s3
	s_add_u32 s100, s44, s24
	s_addc_u32 s101, s45, s25
	global_load_lds_dwordx4 v154, s[38:39]
	s_add_i32 m0, s3, 0x2000
	ds_read_b128 v[214:217], v190 offset:23552
	global_load_lds_dwordx4 v158, s[38:39]
	s_mov_b32 m0, s48
	ds_read_b128 v[210:213], v190 offset:22528
	global_load_lds_dwordx4 v152, s[44:45]
	s_mov_b32 m0, s49
	ds_read_b128 v[206:209], v190 offset:21504
	global_load_lds_dwordx4 v156, s[44:45]
	s_waitcnt vmcnt(8) lgkmcnt(0)
	s_barrier
	v_mfma_f32_16x16x32_bf16 v[60:63], v[128:131], v[174:177], v[60:63]
	v_mfma_f32_16x16x32_bf16 v[56:59], v[136:139], v[174:177], v[56:59]
	v_mfma_f32_16x16x32_bf16 v[44:47], v[128:131], v[194:197], v[44:47]
	v_mfma_f32_16x16x32_bf16 v[40:43], v[136:139], v[194:197], v[40:43]
	v_mfma_f32_16x16x32_bf16 v[28:31], v[128:131], v[202:205], v[28:31]
	v_mfma_f32_16x16x32_bf16 v[24:27], v[136:139], v[202:205], v[24:27]
	v_mfma_f32_16x16x32_bf16 v[12:15], v[128:131], v[210:213], v[12:15]
	v_mfma_f32_16x16x32_bf16 v[8:11], v[136:139], v[210:213], v[8:11]
	v_mfma_f32_16x16x32_bf16 v[60:63], v[132:135], v[178:181], v[60:63]
	v_mfma_f32_16x16x32_bf16 v[56:59], v[140:143], v[178:181], v[56:59]
	v_mfma_f32_16x16x32_bf16 v[44:47], v[132:135], v[198:201], v[44:47]
	v_mfma_f32_16x16x32_bf16 v[40:43], v[140:143], v[198:201], v[40:43]
	v_mfma_f32_16x16x32_bf16 v[28:31], v[132:135], v[206:209], v[28:31]
	v_mfma_f32_16x16x32_bf16 v[24:27], v[140:143], v[206:209], v[24:27]
	v_mfma_f32_16x16x32_bf16 v[12:15], v[132:135], v[214:217], v[12:15]
	v_mfma_f32_16x16x32_bf16 v[8:11], v[140:143], v[214:217], v[8:11]
	v_mfma_f32_16x16x32_bf16 v[52:55], v[144:147], v[174:177], v[52:55]
	v_mfma_f32_16x16x32_bf16 v[48:51], v[166:169], v[174:177], v[48:51]
	v_mfma_f32_16x16x32_bf16 v[36:39], v[144:147], v[194:197], v[36:39]
	v_mfma_f32_16x16x32_bf16 v[32:35], v[166:169], v[194:197], v[32:35]
	v_mfma_f32_16x16x32_bf16 v[20:23], v[144:147], v[202:205], v[20:23]
	v_mfma_f32_16x16x32_bf16 v[16:19], v[166:169], v[202:205], v[16:19]
	v_mfma_f32_16x16x32_bf16 v[4:7], v[144:147], v[210:213], v[4:7]
	v_mfma_f32_16x16x32_bf16 v[0:3], v[166:169], v[210:213], v[0:3]
	v_mfma_f32_16x16x32_bf16 v[52:55], v[148:151], v[178:181], v[52:55]
	v_mfma_f32_16x16x32_bf16 v[48:51], v[170:173], v[178:181], v[48:51]
	v_mfma_f32_16x16x32_bf16 v[36:39], v[148:151], v[198:201], v[36:39]
	v_mfma_f32_16x16x32_bf16 v[32:35], v[170:173], v[198:201], v[32:35]
	v_mfma_f32_16x16x32_bf16 v[20:23], v[148:151], v[206:209], v[20:23]
	v_mfma_f32_16x16x32_bf16 v[16:19], v[170:173], v[206:209], v[16:19]
	v_mfma_f32_16x16x32_bf16 v[4:7], v[148:151], v[214:217], v[4:7]
	v_mfma_f32_16x16x32_bf16 v[0:3], v[170:173], v[214:217], v[0:3]
	s_barrier
	s_add_i32 s3, 0, 0x18000
	s_add_i32 s73, 0, 0x1c000
	v_add_u32_e32 v140, s3, v187
	v_add_u32_e32 v170, s73, v187
	ds_read_b128 v[128:131], v140
	ds_read_b128 v[132:135], v140 offset:1024
	ds_read_b128 v[136:139], v140 offset:2048
	ds_read_b128 v[140:143], v140 offset:3072
	ds_read_b128 v[144:147], v170
	ds_read_b128 v[148:151], v170 offset:1024
	ds_read_b128 v[166:169], v170 offset:2048
	ds_read_b128 v[170:173], v170 offset:3072
	s_add_u32 s38, s44, 0x158000
	s_addc_u32 s39, s45, 0
	s_mov_b32 m0, s51
	ds_read_b128 v[174:177], v190 offset:32768
	ds_read_b128 v[178:181], v190 offset:33792
	ds_read_b128 v[194:197], v190 offset:34816
	ds_read_b128 v[198:201], v190 offset:35840
	ds_read_b128 v[202:205], v190 offset:36864
	ds_read_b128 v[206:209], v190 offset:37888
	ds_read_b128 v[210:213], v190 offset:38912
	global_load_lds_dwordx4 v152, s[38:39]
	s_mov_b32 m0, s52
	ds_read_b128 v[214:217], v190 offset:39936
	global_load_lds_dwordx4 v156, s[38:39]
	s_waitcnt vmcnt(8) lgkmcnt(0)
	s_barrier
	v_mfma_f32_16x16x32_bf16 v[124:127], v[128:131], v[174:177], v[124:127]
	v_mfma_f32_16x16x32_bf16 v[120:123], v[136:139], v[174:177], v[120:123]
	v_mfma_f32_16x16x32_bf16 v[108:111], v[128:131], v[194:197], v[108:111]
	v_mfma_f32_16x16x32_bf16 v[104:107], v[136:139], v[194:197], v[104:107]
	v_mfma_f32_16x16x32_bf16 v[92:95], v[128:131], v[202:205], v[92:95]
	v_mfma_f32_16x16x32_bf16 v[88:91], v[136:139], v[202:205], v[88:91]
	v_mfma_f32_16x16x32_bf16 v[76:79], v[128:131], v[210:213], v[76:79]
	v_mfma_f32_16x16x32_bf16 v[72:75], v[136:139], v[210:213], v[72:75]
	v_mfma_f32_16x16x32_bf16 v[124:127], v[132:135], v[178:181], v[124:127]
	v_mfma_f32_16x16x32_bf16 v[120:123], v[140:143], v[178:181], v[120:123]
	v_mfma_f32_16x16x32_bf16 v[108:111], v[132:135], v[198:201], v[108:111]
	v_mfma_f32_16x16x32_bf16 v[104:107], v[140:143], v[198:201], v[104:107]
	v_mfma_f32_16x16x32_bf16 v[92:95], v[132:135], v[206:209], v[92:95]
	v_mfma_f32_16x16x32_bf16 v[88:91], v[140:143], v[206:209], v[88:91]
	v_mfma_f32_16x16x32_bf16 v[76:79], v[132:135], v[214:217], v[76:79]
	v_mfma_f32_16x16x32_bf16 v[72:75], v[140:143], v[214:217], v[72:75]
	v_mfma_f32_16x16x32_bf16 v[116:119], v[144:147], v[174:177], v[116:119]
	v_mfma_f32_16x16x32_bf16 v[112:115], v[166:169], v[174:177], v[112:115]
	v_mfma_f32_16x16x32_bf16 v[100:103], v[144:147], v[194:197], v[100:103]
	v_mfma_f32_16x16x32_bf16 v[96:99], v[166:169], v[194:197], v[96:99]
	v_mfma_f32_16x16x32_bf16 v[84:87], v[144:147], v[202:205], v[84:87]
	v_mfma_f32_16x16x32_bf16 v[80:83], v[166:169], v[202:205], v[80:83]
	v_mfma_f32_16x16x32_bf16 v[68:71], v[144:147], v[210:213], v[68:71]
	v_mfma_f32_16x16x32_bf16 v[64:67], v[166:169], v[210:213], v[64:67]
	v_mfma_f32_16x16x32_bf16 v[116:119], v[148:151], v[178:181], v[116:119]
	v_mfma_f32_16x16x32_bf16 v[112:115], v[170:173], v[178:181], v[112:115]
	v_mfma_f32_16x16x32_bf16 v[100:103], v[148:151], v[198:201], v[100:103]
	v_mfma_f32_16x16x32_bf16 v[96:99], v[170:173], v[198:201], v[96:99]
	v_mfma_f32_16x16x32_bf16 v[84:87], v[148:151], v[206:209], v[84:87]
	v_mfma_f32_16x16x32_bf16 v[80:83], v[170:173], v[206:209], v[80:83]
	v_mfma_f32_16x16x32_bf16 v[68:71], v[148:151], v[214:217], v[68:71]
	v_mfma_f32_16x16x32_bf16 v[64:67], v[170:173], v[214:217], v[64:67]
	s_barrier
	s_add_i32 s3, s3, s33
	s_mov_b32 m0, s3
	ds_read_b128 v[174:177], v190 offset:49152
	ds_read_b128 v[178:181], v190 offset:50176
	ds_read_b128 v[194:197], v190 offset:51200
	ds_read_b128 v[198:201], v190 offset:52224
	global_load_lds_dwordx4 v154, s[98:99]
	s_add_i32 m0, s3, 0x2000
	s_add_u32 s38, s42, 0x158080
	s_addc_u32 s39, s43, 0
	s_add_i32 s3, s73, s33
	global_load_lds_dwordx4 v158, s[98:99]
	s_mov_b32 m0, s3
	ds_read_b128 v[214:217], v190 offset:56320
	global_load_lds_dwordx4 v154, s[38:39]
	s_add_i32 m0, s3, 0x2000
	ds_read_b128 v[210:213], v190 offset:55296
	global_load_lds_dwordx4 v158, s[38:39]
	s_mov_b32 m0, s56
	ds_read_b128 v[206:209], v190 offset:54272
	global_load_lds_dwordx4 v152, s[100:101]
	s_mov_b32 m0, s57
	ds_read_b128 v[202:205], v190 offset:53248
	global_load_lds_dwordx4 v156, s[100:101]
	s_waitcnt vmcnt(8) lgkmcnt(0)
	s_barrier
	v_mfma_f32_16x16x32_bf16 v[60:63], v[128:131], v[174:177], v[60:63]
	v_mfma_f32_16x16x32_bf16 v[56:59], v[136:139], v[174:177], v[56:59]
	v_mfma_f32_16x16x32_bf16 v[44:47], v[128:131], v[194:197], v[44:47]
	v_mfma_f32_16x16x32_bf16 v[40:43], v[136:139], v[194:197], v[40:43]
	v_mfma_f32_16x16x32_bf16 v[28:31], v[128:131], v[202:205], v[28:31]
	v_mfma_f32_16x16x32_bf16 v[24:27], v[136:139], v[202:205], v[24:27]
	v_mfma_f32_16x16x32_bf16 v[12:15], v[128:131], v[210:213], v[12:15]
	v_mfma_f32_16x16x32_bf16 v[8:11], v[136:139], v[210:213], v[8:11]
	v_mfma_f32_16x16x32_bf16 v[60:63], v[132:135], v[178:181], v[60:63]
	v_mfma_f32_16x16x32_bf16 v[56:59], v[140:143], v[178:181], v[56:59]
	v_mfma_f32_16x16x32_bf16 v[44:47], v[132:135], v[198:201], v[44:47]
	v_mfma_f32_16x16x32_bf16 v[40:43], v[140:143], v[198:201], v[40:43]
	v_mfma_f32_16x16x32_bf16 v[28:31], v[132:135], v[206:209], v[28:31]
	v_mfma_f32_16x16x32_bf16 v[24:27], v[140:143], v[206:209], v[24:27]
	v_mfma_f32_16x16x32_bf16 v[12:15], v[132:135], v[214:217], v[12:15]
	v_mfma_f32_16x16x32_bf16 v[8:11], v[140:143], v[214:217], v[8:11]
	v_mfma_f32_16x16x32_bf16 v[52:55], v[144:147], v[174:177], v[52:55]
	v_mfma_f32_16x16x32_bf16 v[48:51], v[166:169], v[174:177], v[48:51]
	v_mfma_f32_16x16x32_bf16 v[36:39], v[144:147], v[194:197], v[36:39]
	v_mfma_f32_16x16x32_bf16 v[32:35], v[166:169], v[194:197], v[32:35]
	v_mfma_f32_16x16x32_bf16 v[20:23], v[144:147], v[202:205], v[20:23]
	v_mfma_f32_16x16x32_bf16 v[16:19], v[166:169], v[202:205], v[16:19]
	v_mfma_f32_16x16x32_bf16 v[4:7], v[144:147], v[210:213], v[4:7]
	v_mfma_f32_16x16x32_bf16 v[0:3], v[166:169], v[210:213], v[0:3]
	v_mfma_f32_16x16x32_bf16 v[52:55], v[148:151], v[178:181], v[52:55]
	v_mfma_f32_16x16x32_bf16 v[48:51], v[170:173], v[178:181], v[48:51]
	v_mfma_f32_16x16x32_bf16 v[36:39], v[148:151], v[198:201], v[36:39]
	v_mfma_f32_16x16x32_bf16 v[32:35], v[170:173], v[198:201], v[32:35]
	v_mfma_f32_16x16x32_bf16 v[20:23], v[148:151], v[206:209], v[20:23]
	v_mfma_f32_16x16x32_bf16 v[16:19], v[170:173], v[206:209], v[16:19]
	v_mfma_f32_16x16x32_bf16 v[4:7], v[148:151], v[214:217], v[4:7]
	v_mfma_f32_16x16x32_bf16 v[0:3], v[170:173], v[214:217], v[0:3]
	s_barrier
	s_add_i32 s1, s1, 2
	s_add_u32 s4, s4, 0x100
	s_addc_u32 s5, s5, 0
	s_cmpk_gt_u32 s1, 0x53
	s_mov_b64 s[38:39], s[40:41]
	s_cbranch_scc0 .LBB0_876
	s_and_b64 vcc, exec, s[26:27]
	s_cbranch_vccz .LBB0_879
	s_barrier
